# adds the F (up-projection) epilogue rewrite on top of local barriers + qk epilogue rewrite
# baseline (speedup 1.0000x reference)
; DI unsigned pk2(float a, float b) { f32x2 v = {a, b}; bf2_t r = __builtin_convertvector(v, bf2_t); return __builtin_bit_cast(unsigned, r); }
; DI float bf_lo(unsigned u) { return __uint_as_float(u << 16); }
; DI float bf_hi(unsigned u) { return __uint_as_float(u & 0xffff0000u); }
; DI void gemm_up_pass_big(const bf16_t* Y, const bf16_t* W, const bf16_t* __restrict__ GBR, int gcol0, bf16_t* __restrict__ MG, bool first,
;                          int mt, int nt, char* smem) {
;     ...
;     const int r = tid >> 4, ch = tid & 15;
; #pragma unroll 2
;     for (int ps = 0; ps < 8; ++ps) {
;       const int row = ps * 16 + r;
;       const float4 a0 = *(const float4*)(st + row * 132 + ch * 8), a1 = *(const float4*)(st + row * 132 + ch * 8 + 4);
;       const size_t grow = (size_t)(m0 + h * 128 + row);
;       const u32x4 gv = *(const u32x4*)(GBR + grow * 2048 + gcol0 + n0 + ch * 8);
;       float v[8];
;       v[0] = bf_lo(gv.x) * a0.x; v[1] = bf_hi(gv.x) * a0.y; v[2] = bf_lo(gv.y) * a0.z; v[3] = bf_hi(gv.y) * a0.w;
;       v[4] = bf_lo(gv.z) * a1.x; v[5] = bf_hi(gv.z) * a1.y; v[6] = bf_lo(gv.w) * a1.z; v[7] = bf_hi(gv.w) * a1.w;
;       bf16_t* mp = MG + grow * 1024 + n0 + ch * 8;
;       if (!first) {
;         const u32x4 pv = *(const u32x4*)mp;
;         v[0] += bf_lo(pv.x); v[1] += bf_hi(pv.x); v[2] += bf_lo(pv.y); v[3] += bf_hi(pv.y);
;         v[4] += bf_lo(pv.z); v[5] += bf_hi(pv.z); v[6] += bf_lo(pv.w); v[7] += bf_hi(pv.w);
;       }
;       u32x4 ov; ov.x = pk2(v[0], v[1]); ov.y = pk2(v[2], v[3]); ov.z = pk2(v[4], v[5]); ov.w = pk2(v[6], v[7]);
;       *(u32x4*)mp = ov;
.LBB0_1047:
	v_lshl_add_u64 v[194:195], v[136:137], 0, s[28:29]
	v_lshl_add_u64 v[196:197], v[132:133], 0, s[28:29]
	v_lshl_add_u64 v[202:203], v[134:135], 0, s[28:29]
	v_lshl_add_u64 v[204:205], v[130:131], 0, s[28:29]
	global_load_dwordx4 v[138:141], v[194:195], off
	v_lshl_add_u64 v[194:195], v[194:195], 0, s[92:93]
	global_load_dwordx4 v[142:145], v[196:197], off
	v_lshl_add_u64 v[196:197], v[196:197], 0, s[92:93]
	global_load_dwordx4 v[146:149], v[194:195], off
	v_lshl_add_u64 v[194:195], v[194:195], 0, s[92:93]
	global_load_dwordx4 v[150:153], v[196:197], off
	v_lshl_add_u64 v[196:197], v[196:197], 0, s[92:93]
	ds_read_b128 v[172:175], v0 offset:0
	ds_read_b128 v[176:179], v0 offset:16
	s_waitcnt vmcnt(3) lgkmcnt(0)
	v_lshlrev_b32_e32 v190, 16, v138
	v_and_b32_e32 v191, 0xffff0000, v138
	v_pk_mul_f32 v[172:173], v[172:173], v[190:191]
	v_lshlrev_b32_e32 v190, 16, v139
	v_and_b32_e32 v191, 0xffff0000, v139
	v_pk_mul_f32 v[174:175], v[174:175], v[190:191]
	v_lshlrev_b32_e32 v190, 16, v140
	v_and_b32_e32 v191, 0xffff0000, v140
	v_pk_mul_f32 v[176:177], v[176:177], v[190:191]
	v_lshlrev_b32_e32 v190, 16, v141
	v_and_b32_e32 v191, 0xffff0000, v141
	v_pk_mul_f32 v[178:179], v[178:179], v[190:191]
	v_cvt_pk_bf16_f32 v186, v172, v173
	v_cvt_pk_bf16_f32 v187, v174, v175
	v_cvt_pk_bf16_f32 v188, v176, v177
	v_cvt_pk_bf16_f32 v189, v178, v179
	global_store_dwordx4 v[202:203], v[186:189], off
	s_nop 1
	v_lshl_add_u64 v[202:203], v[202:203], 0, s[38:39]
	ds_read_b128 v[172:175], v0 offset:8448
	ds_read_b128 v[176:179], v0 offset:8464
	s_waitcnt vmcnt(3) lgkmcnt(0)
	v_lshlrev_b32_e32 v190, 16, v142
	v_and_b32_e32 v191, 0xffff0000, v142
	v_pk_mul_f32 v[172:173], v[172:173], v[190:191]
	v_lshlrev_b32_e32 v190, 16, v143
	v_and_b32_e32 v191, 0xffff0000, v143
	v_pk_mul_f32 v[174:175], v[174:175], v[190:191]
	v_lshlrev_b32_e32 v190, 16, v144
	v_and_b32_e32 v191, 0xffff0000, v144
	v_pk_mul_f32 v[176:177], v[176:177], v[190:191]
	v_lshlrev_b32_e32 v190, 16, v145
	v_and_b32_e32 v191, 0xffff0000, v145
	v_pk_mul_f32 v[178:179], v[178:179], v[190:191]
	v_cvt_pk_bf16_f32 v186, v172, v173
	v_cvt_pk_bf16_f32 v187, v174, v175
	v_cvt_pk_bf16_f32 v188, v176, v177
	v_cvt_pk_bf16_f32 v189, v178, v179
	global_store_dwordx4 v[204:205], v[186:189], off
	s_nop 1
	v_lshl_add_u64 v[204:205], v[204:205], 0, s[38:39]
	ds_read_b128 v[172:175], v0 offset:16896
	ds_read_b128 v[176:179], v0 offset:16912
	s_waitcnt vmcnt(3) lgkmcnt(0)
	v_lshlrev_b32_e32 v190, 16, v146
	v_and_b32_e32 v191, 0xffff0000, v146
	v_pk_mul_f32 v[172:173], v[172:173], v[190:191]
	v_lshlrev_b32_e32 v190, 16, v147
	v_and_b32_e32 v191, 0xffff0000, v147
	v_pk_mul_f32 v[174:175], v[174:175], v[190:191]
	v_lshlrev_b32_e32 v190, 16, v148
	v_and_b32_e32 v191, 0xffff0000, v148
	v_pk_mul_f32 v[176:177], v[176:177], v[190:191]
	v_lshlrev_b32_e32 v190, 16, v149
	v_and_b32_e32 v191, 0xffff0000, v149
	v_pk_mul_f32 v[178:179], v[178:179], v[190:191]
	v_cvt_pk_bf16_f32 v186, v172, v173
	v_cvt_pk_bf16_f32 v187, v174, v175
	v_cvt_pk_bf16_f32 v188, v176, v177
	v_cvt_pk_bf16_f32 v189, v178, v179
	global_store_dwordx4 v[202:203], v[186:189], off
	s_nop 1
	v_lshl_add_u64 v[202:203], v[202:203], 0, s[38:39]
	ds_read_b128 v[172:175], v0 offset:25344
	ds_read_b128 v[176:179], v0 offset:25360
	s_waitcnt vmcnt(3) lgkmcnt(0)
	v_lshlrev_b32_e32 v190, 16, v150
	v_and_b32_e32 v191, 0xffff0000, v150
	v_pk_mul_f32 v[172:173], v[172:173], v[190:191]
	v_lshlrev_b32_e32 v190, 16, v151
	v_and_b32_e32 v191, 0xffff0000, v151
	v_pk_mul_f32 v[174:175], v[174:175], v[190:191]
	v_lshlrev_b32_e32 v190, 16, v152
	v_and_b32_e32 v191, 0xffff0000, v152
	v_pk_mul_f32 v[176:177], v[176:177], v[190:191]
	v_lshlrev_b32_e32 v190, 16, v153
	v_and_b32_e32 v191, 0xffff0000, v153
	v_pk_mul_f32 v[178:179], v[178:179], v[190:191]
	v_cvt_pk_bf16_f32 v186, v172, v173
	v_cvt_pk_bf16_f32 v187, v174, v175
	v_cvt_pk_bf16_f32 v188, v176, v177
	v_cvt_pk_bf16_f32 v189, v178, v179
	global_store_dwordx4 v[204:205], v[186:189], off
	s_nop 1
	v_lshl_add_u64 v[204:205], v[204:205], 0, s[38:39]
	global_load_dwordx4 v[138:141], v[194:195], off
	v_lshl_add_u64 v[194:195], v[194:195], 0, s[92:93]
	global_load_dwordx4 v[142:145], v[196:197], off
	v_lshl_add_u64 v[196:197], v[196:197], 0, s[92:93]
	global_load_dwordx4 v[146:149], v[194:195], off
	v_lshl_add_u64 v[194:195], v[194:195], 0, s[92:93]
	global_load_dwordx4 v[150:153], v[196:197], off
	v_lshl_add_u64 v[196:197], v[196:197], 0, s[92:93]
	ds_read_b128 v[172:175], v0 offset:33792
	ds_read_b128 v[176:179], v0 offset:33808
	s_waitcnt vmcnt(3) lgkmcnt(0)
	v_lshlrev_b32_e32 v190, 16, v138
	v_and_b32_e32 v191, 0xffff0000, v138
	v_pk_mul_f32 v[172:173], v[172:173], v[190:191]
	v_lshlrev_b32_e32 v190, 16, v139
	v_and_b32_e32 v191, 0xffff0000, v139
	v_pk_mul_f32 v[174:175], v[174:175], v[190:191]
	v_lshlrev_b32_e32 v190, 16, v140
	v_and_b32_e32 v191, 0xffff0000, v140
	v_pk_mul_f32 v[176:177], v[176:177], v[190:191]
	v_lshlrev_b32_e32 v190, 16, v141
	v_and_b32_e32 v191, 0xffff0000, v141
	v_pk_mul_f32 v[178:179], v[178:179], v[190:191]
	v_cvt_pk_bf16_f32 v186, v172, v173
	v_cvt_pk_bf16_f32 v187, v174, v175
	v_cvt_pk_bf16_f32 v188, v176, v177
	v_cvt_pk_bf16_f32 v189, v178, v179
	global_store_dwordx4 v[202:203], v[186:189], off
	s_nop 1
	v_lshl_add_u64 v[202:203], v[202:203], 0, s[38:39]
	ds_read_b128 v[172:175], v0 offset:42240
	ds_read_b128 v[176:179], v0 offset:42256
	s_waitcnt vmcnt(3) lgkmcnt(0)
; DI unsigned pk2(float a, float b) { f32x2 v = {a, b}; bf2_t r = __builtin_convertvector(v, bf2_t); return __builtin_bit_cast(unsigned, r); }
; DI float bf_lo(unsigned u) { return __uint_as_float(u << 16); }
; DI float bf_hi(unsigned u) { return __uint_as_float(u & 0xffff0000u); }
; DI void stage_half(float* st, const f32x16 (&acc)[4][2], int h, int tid) {
;   const int lane = tid & 63, w = tid >> 6, wm = w >> 1, wn = w & 1, c = lane & 31, half = lane >> 5;
;   if (wm == h) {
; DI void gemm_up_pass_big(const bf16_t* Y, const bf16_t* W, const bf16_t* __restrict__ GBR, int gcol0, bf16_t* __restrict__ MG, bool first,
;                          int mt, int nt, char* smem) {
;     ...
; #pragma unroll 2
;     for (int ps = 0; ps < 8; ++ps) {
;       const int row = ps * 16 + r;
;       const float4 a0 = *(const float4*)(st + row * 132 + ch * 8), a1 = *(const float4*)(st + row * 132 + ch * 8 + 4);
;       const size_t grow = (size_t)(m0 + h * 128 + row);
;       const u32x4 gv = *(const u32x4*)(GBR + grow * 2048 + gcol0 + n0 + ch * 8);
;       float v[8];
;       v[0] = bf_lo(gv.x) * a0.x; v[1] = bf_hi(gv.x) * a0.y; v[2] = bf_lo(gv.y) * a0.z; v[3] = bf_hi(gv.y) * a0.w;
;       v[4] = bf_lo(gv.z) * a1.x; v[5] = bf_hi(gv.z) * a1.y; v[6] = bf_lo(gv.w) * a1.z; v[7] = bf_hi(gv.w) * a1.w;
;       bf16_t* mp = MG + grow * 1024 + n0 + ch * 8;
;       if (!first) {
;         const u32x4 pv = *(const u32x4*)mp;
;         v[0] += bf_lo(pv.x); v[1] += bf_hi(pv.x); v[2] += bf_lo(pv.y); v[3] += bf_hi(pv.y);
;         v[4] += bf_lo(pv.z); v[5] += bf_hi(pv.z); v[6] += bf_lo(pv.w); v[7] += bf_hi(pv.w);
;       }
;       u32x4 ov; ov.x = pk2(v[0], v[1]); ov.y = pk2(v[2], v[3]); ov.z = pk2(v[4], v[5]); ov.w = pk2(v[6], v[7]);
;       *(u32x4*)mp = ov;
;     }
;     __syncthreads();
	v_lshlrev_b32_e32 v190, 16, v142
	v_and_b32_e32 v191, 0xffff0000, v142
	v_pk_mul_f32 v[172:173], v[172:173], v[190:191]
	v_lshlrev_b32_e32 v190, 16, v143
	v_and_b32_e32 v191, 0xffff0000, v143
	v_pk_mul_f32 v[174:175], v[174:175], v[190:191]
	v_lshlrev_b32_e32 v190, 16, v144
	v_and_b32_e32 v191, 0xffff0000, v144
	v_pk_mul_f32 v[176:177], v[176:177], v[190:191]
	v_lshlrev_b32_e32 v190, 16, v145
	v_and_b32_e32 v191, 0xffff0000, v145
	v_pk_mul_f32 v[178:179], v[178:179], v[190:191]
	v_cvt_pk_bf16_f32 v186, v172, v173
	v_cvt_pk_bf16_f32 v187, v174, v175
	v_cvt_pk_bf16_f32 v188, v176, v177
	v_cvt_pk_bf16_f32 v189, v178, v179
	global_store_dwordx4 v[204:205], v[186:189], off
	s_nop 1
	v_lshl_add_u64 v[204:205], v[204:205], 0, s[38:39]
	ds_read_b128 v[172:175], v0 offset:50688
	ds_read_b128 v[176:179], v0 offset:50704
	s_waitcnt vmcnt(3) lgkmcnt(0)
	v_lshlrev_b32_e32 v190, 16, v146
	v_and_b32_e32 v191, 0xffff0000, v146
	v_pk_mul_f32 v[172:173], v[172:173], v[190:191]
	v_lshlrev_b32_e32 v190, 16, v147
	v_and_b32_e32 v191, 0xffff0000, v147
	v_pk_mul_f32 v[174:175], v[174:175], v[190:191]
	v_lshlrev_b32_e32 v190, 16, v148
	v_and_b32_e32 v191, 0xffff0000, v148
	v_pk_mul_f32 v[176:177], v[176:177], v[190:191]
	v_lshlrev_b32_e32 v190, 16, v149
	v_and_b32_e32 v191, 0xffff0000, v149
	v_pk_mul_f32 v[178:179], v[178:179], v[190:191]
	v_cvt_pk_bf16_f32 v186, v172, v173
	v_cvt_pk_bf16_f32 v187, v174, v175
	v_cvt_pk_bf16_f32 v188, v176, v177
	v_cvt_pk_bf16_f32 v189, v178, v179
	global_store_dwordx4 v[202:203], v[186:189], off
	s_nop 1
	v_lshl_add_u64 v[202:203], v[202:203], 0, s[38:39]
	ds_read_b128 v[172:175], v0 offset:59136
	ds_read_b128 v[176:179], v0 offset:59152
	s_waitcnt vmcnt(3) lgkmcnt(0)
	v_lshlrev_b32_e32 v190, 16, v150
	v_and_b32_e32 v191, 0xffff0000, v150
	v_pk_mul_f32 v[172:173], v[172:173], v[190:191]
	v_lshlrev_b32_e32 v190, 16, v151
	v_and_b32_e32 v191, 0xffff0000, v151
	v_pk_mul_f32 v[174:175], v[174:175], v[190:191]
	v_lshlrev_b32_e32 v190, 16, v152
	v_and_b32_e32 v191, 0xffff0000, v152
	v_pk_mul_f32 v[176:177], v[176:177], v[190:191]
	v_lshlrev_b32_e32 v190, 16, v153
	v_and_b32_e32 v191, 0xffff0000, v153
	v_pk_mul_f32 v[178:179], v[178:179], v[190:191]
	v_cvt_pk_bf16_f32 v186, v172, v173
	v_cvt_pk_bf16_f32 v187, v174, v175
	v_cvt_pk_bf16_f32 v188, v176, v177
	v_cvt_pk_bf16_f32 v189, v178, v179
	global_store_dwordx4 v[204:205], v[186:189], off
	s_nop 1
	v_lshl_add_u64 v[204:205], v[204:205], 0, s[38:39]
	v_mov_b32_e32 v0, v216
	s_barrier
	s_nop 0
	v_and_b32_e32 v130, 0xffffff80, v0
	v_cmp_eq_u32_e32 vcc, s31, v130
	s_and_saveexec_b64 s[42:43], vcc
	s_cbranch_execz .LBB0_1050
; DI int crow(int i, int h) { return (i & 3) + 8 * (i >> 2) + 4 * h; }
; DI void stage_half(float* st, const f32x16 (&acc)[4][2], int h, int tid) {
;   const int lane = tid & 63, w = tid >> 6, wm = w >> 1, wn = w & 1, c = lane & 31, half = lane >> 5;
;   if (wm == h) {
; #pragma unroll
;     for (int mf = 0; mf < 4; ++mf)
; #pragma unroll
;       for (int nf = 0; nf < 2; ++nf)
; #pragma unroll
;         for (int i = 0; i < 16; ++i) st[(mf * 32 + crow(i, half)) * 132 + wn * 64 + nf * 32 + c] = acc[mf][nf][i];
;   }
	v_lshrrev_b32_e32 v130, 3, v0
	v_and_b32_e32 v130, 4, v130
	v_and_b32_e32 v131, 0x5f, v0
	v_mul_u32_u24_e32 v130, 0x210, v130
	v_lshl_add_u32 v130, v131, 2, v130
	ds_write2_b32 v130, v98, v114 offset1:32
	ds_write2_b32 v130, v99, v115 offset0:132 offset1:164
	v_add_u32_e32 v98, 0x400, v130
	ds_write2_b32 v98, v100, v116 offset0:8 offset1:40
	ds_write2_b32 v98, v101, v117 offset0:140 offset1:172
	v_add_u32_e32 v98, 0x1000, v130
	ds_write2_b32 v98, v102, v118 offset0:32 offset1:64
	ds_write2_b32 v98, v103, v119 offset0:164 offset1:196
	v_add_u32_e32 v98, 0x1400, v130
	ds_write2_b32 v98, v104, v120 offset0:40 offset1:72
	ds_write2_b32 v98, v105, v121 offset0:172 offset1:204
	v_add_u32_e32 v98, 0x2000, v130
	ds_write2_b32 v98, v106, v122 offset0:64 offset1:96
	ds_write2_b32 v98, v107, v123 offset0:196 offset1:228
	v_add_u32_e32 v98, 0x2400, v130
	ds_write2_b32 v98, v108, v124 offset0:72 offset1:104
	ds_write2_b32 v98, v109, v125 offset0:204 offset1:236
	v_add_u32_e32 v98, 0x3000, v130
	ds_write2_b32 v98, v110, v126 offset0:96 offset1:128
	v_add_u32_e32 v98, 0x3200, v130
	ds_write2_b32 v98, v111, v127 offset0:100 offset1:132
	v_add_u32_e32 v98, 0x3400, v130
	ds_write2_b32 v98, v112, v128 offset0:104 offset1:136
	v_add_u32_e32 v98, 0x3600, v130
	ds_write2_b32 v98, v113, v129 offset0:108 offset1:140
	v_add_u32_e32 v98, 0x4000, v130
	ds_write2_b32 v98, v66, v82 offset0:128 offset1:160
	v_add_u32_e32 v66, 0x4400, v130
	ds_write2_b32 v66, v67, v83 offset0:4 offset1:36
	ds_write2_b32 v66, v68, v84 offset0:136 offset1:168
	v_add_u32_e32 v66, 0x4800, v130
	ds_write2_b32 v66, v69, v85 offset0:12 offset1:44
	v_add_u32_e32 v66, 0x5000, v130
	ds_write2_b32 v66, v70, v86 offset0:160 offset1:192
	v_add_u32_e32 v66, 0x5400, v130
	ds_write2_b32 v66, v71, v87 offset0:36 offset1:68
	ds_write2_b32 v66, v72, v88 offset0:168 offset1:200
	v_add_u32_e32 v66, 0x5800, v130
	ds_write2_b32 v66, v73, v89 offset0:44 offset1:76
	v_add_u32_e32 v66, 0x6000, v130
	ds_write2_b32 v66, v74, v90 offset0:192 offset1:224
	v_add_u32_e32 v66, 0x6400, v130
	ds_write2_b32 v66, v75, v91 offset0:68 offset1:100
	ds_write2_b32 v66, v76, v92 offset0:200 offset1:232
	v_add_u32_e32 v66, 0x6800, v130
	ds_write2_b32 v66, v77, v93 offset0:76 offset1:108
	v_add_u32_e32 v66, 0x7200, v130
	ds_write2_b32 v66, v78, v94 offset0:96 offset1:128
	v_add_u32_e32 v66, 0x7400, v130
	ds_write2_b32 v66, v79, v95 offset0:100 offset1:132
	v_add_u32_e32 v66, 0x7600, v130
	ds_write2_b32 v66, v80, v96 offset0:104 offset1:136
	v_add_u32_e32 v66, 0x7800, v130
	ds_write2_b32 v66, v81, v97 offset0:108 offset1:140
	v_add_u32_e32 v66, 0x8400, v130
	ds_write2_b32 v66, v34, v50 offset1:32
	ds_write2_b32 v66, v35, v51 offset0:132 offset1:164
	v_add_u32_e32 v34, 0x8800, v130
	ds_write2_b32 v34, v36, v52 offset0:8 offset1:40
	ds_write2_b32 v34, v37, v53 offset0:140 offset1:172
	v_add_u32_e32 v34, 0x9400, v130
	ds_write2_b32 v34, v38, v54 offset0:32 offset1:64
	ds_write2_b32 v34, v39, v55 offset0:164 offset1:196
	v_add_u32_e32 v34, 0x9800, v130
	ds_write2_b32 v34, v40, v56 offset0:40 offset1:72
	ds_write2_b32 v34, v41, v57 offset0:172 offset1:204
	v_add_u32_e32 v34, 0xa400, v130
	ds_write2_b32 v34, v42, v58 offset0:64 offset1:96
	ds_write2_b32 v34, v43, v59 offset0:196 offset1:228
	v_add_u32_e32 v34, 0xa800, v130
	ds_write2_b32 v34, v44, v60 offset0:72 offset1:104
	ds_write2_b32 v34, v45, v61 offset0:204 offset1:236
	v_add_u32_e32 v34, 0xb400, v130
	ds_write2_b32 v34, v46, v62 offset0:96 offset1:128
	v_add_u32_e32 v34, 0xb600, v130
	ds_write2_b32 v34, v47, v63 offset0:100 offset1:132
	v_add_u32_e32 v34, 0xb800, v130
	ds_write2_b32 v34, v48, v64 offset0:104 offset1:136
	v_add_u32_e32 v34, 0xba00, v130
	ds_write2_b32 v34, v49, v65 offset0:108 offset1:140
	v_add_u32_e32 v34, 0xc400, v130
	ds_write2_b32 v34, v2, v18 offset0:128 offset1:160
	v_add_u32_e32 v2, 0xc800, v130
	ds_write2_b32 v2, v3, v19 offset0:4 offset1:36
	ds_write2_b32 v2, v4, v20 offset0:136 offset1:168
	v_add_u32_e32 v2, 0xcc00, v130
	ds_write2_b32 v2, v5, v21 offset0:12 offset1:44
	v_add_u32_e32 v2, 0xd400, v130
	ds_write2_b32 v2, v6, v22 offset0:160 offset1:192
	v_add_u32_e32 v2, 0xd800, v130
	ds_write2_b32 v2, v7, v23 offset0:36 offset1:68
	ds_write2_b32 v2, v8, v24 offset0:168 offset1:200
	v_add_u32_e32 v2, 0xdc00, v130
	ds_write2_b32 v2, v9, v25 offset0:44 offset1:76
	v_add_u32_e32 v2, 0xe400, v130
	ds_write2_b32 v2, v10, v26 offset0:192 offset1:224
	v_add_u32_e32 v2, 0xe800, v130
	ds_write2_b32 v2, v11, v27 offset0:68 offset1:100
	ds_write2_b32 v2, v12, v28 offset0:200 offset1:232
	v_add_u32_e32 v2, 0xec00, v130
	ds_write2_b32 v2, v13, v29 offset0:76 offset1:108
	v_add_u32_e32 v2, 0xf600, v130
	ds_write2_b32 v2, v14, v30 offset0:96 offset1:128
	v_add_u32_e32 v2, 0xf800, v130
	ds_write2_b32 v2, v15, v31 offset0:100 offset1:132
	v_add_u32_e32 v2, 0xfa00, v130
	ds_write2_b32 v2, v16, v32 offset0:104 offset1:136
	v_add_u32_e32 v2, 0xfc00, v130
	ds_write2_b32 v2, v17, v33 offset0:108 offset1:140

; DI unsigned pk2(float a, float b) { f32x2 v = {a, b}; bf2_t r = __builtin_convertvector(v, bf2_t); return __builtin_bit_cast(unsigned, r); }
; DI float bf_lo(unsigned u) { return __uint_as_float(u << 16); }
; DI float bf_hi(unsigned u) { return __uint_as_float(u & 0xffff0000u); }
; DI void gemm_up_pass_big(const bf16_t* Y, const bf16_t* W, const bf16_t* __restrict__ GBR, int gcol0, bf16_t* __restrict__ MG, bool first,
;                          int mt, int nt, char* smem) {
;     ...
;     const int r = tid >> 4, ch = tid & 15;
; #pragma unroll 2
;     for (int ps = 0; ps < 8; ++ps) {
;       const int row = ps * 16 + r;
;       const float4 a0 = *(const float4*)(st + row * 132 + ch * 8), a1 = *(const float4*)(st + row * 132 + ch * 8 + 4);
;       const size_t grow = (size_t)(m0 + h * 128 + row);
;       const u32x4 gv = *(const u32x4*)(GBR + grow * 2048 + gcol0 + n0 + ch * 8);
;       float v[8];
;       v[0] = bf_lo(gv.x) * a0.x; v[1] = bf_hi(gv.x) * a0.y; v[2] = bf_lo(gv.y) * a0.z; v[3] = bf_hi(gv.y) * a0.w;
;       v[4] = bf_lo(gv.z) * a1.x; v[5] = bf_hi(gv.z) * a1.y; v[6] = bf_lo(gv.w) * a1.z; v[7] = bf_hi(gv.w) * a1.w;
;       bf16_t* mp = MG + grow * 1024 + n0 + ch * 8;
;       if (!first) {
;         const u32x4 pv = *(const u32x4*)mp;
;         v[0] += bf_lo(pv.x); v[1] += bf_hi(pv.x); v[2] += bf_lo(pv.y); v[3] += bf_hi(pv.y);
;         v[4] += bf_lo(pv.z); v[5] += bf_hi(pv.z); v[6] += bf_lo(pv.w); v[7] += bf_hi(pv.w);
;       }
;       u32x4 ov; ov.x = pk2(v[0], v[1]); ov.y = pk2(v[2], v[3]); ov.z = pk2(v[4], v[5]); ov.w = pk2(v[6], v[7]);
;       *(u32x4*)mp = ov;
;     }
.LBB0_1051:
	v_lshl_add_u64 v[194:195], v[8:9], 0, s[28:29]
	v_lshl_add_u64 v[196:197], v[4:5], 0, s[28:29]
	v_lshl_add_u64 v[202:203], v[6:7], 0, s[28:29]
	v_lshl_add_u64 v[204:205], v[2:3], 0, s[28:29]
	global_load_dwordx4 v[138:141], v[194:195], off
	v_lshl_add_u64 v[194:195], v[194:195], 0, s[92:93]
	global_load_dwordx4 v[142:145], v[196:197], off
	v_lshl_add_u64 v[196:197], v[196:197], 0, s[92:93]
	global_load_dwordx4 v[146:149], v[194:195], off
	v_lshl_add_u64 v[194:195], v[194:195], 0, s[92:93]
	global_load_dwordx4 v[150:153], v[196:197], off
	v_lshl_add_u64 v[196:197], v[196:197], 0, s[92:93]
	ds_read_b128 v[172:175], v0 offset:0
	ds_read_b128 v[176:179], v0 offset:16
	s_waitcnt vmcnt(3) lgkmcnt(0)
	v_lshlrev_b32_e32 v190, 16, v138
	v_and_b32_e32 v191, 0xffff0000, v138
	v_pk_mul_f32 v[172:173], v[172:173], v[190:191]
	v_lshlrev_b32_e32 v190, 16, v139
	v_and_b32_e32 v191, 0xffff0000, v139
	v_pk_mul_f32 v[174:175], v[174:175], v[190:191]
	v_lshlrev_b32_e32 v190, 16, v140
	v_and_b32_e32 v191, 0xffff0000, v140
	v_pk_mul_f32 v[176:177], v[176:177], v[190:191]
	v_lshlrev_b32_e32 v190, 16, v141
	v_and_b32_e32 v191, 0xffff0000, v141
	v_pk_mul_f32 v[178:179], v[178:179], v[190:191]
	v_cvt_pk_bf16_f32 v186, v172, v173
	v_cvt_pk_bf16_f32 v187, v174, v175
	v_cvt_pk_bf16_f32 v188, v176, v177
	v_cvt_pk_bf16_f32 v189, v178, v179
	global_store_dwordx4 v[202:203], v[186:189], off
	s_nop 1
	v_lshl_add_u64 v[202:203], v[202:203], 0, s[38:39]
	ds_read_b128 v[172:175], v0 offset:8448
	ds_read_b128 v[176:179], v0 offset:8464
	s_waitcnt vmcnt(3) lgkmcnt(0)
	v_lshlrev_b32_e32 v190, 16, v142
	v_and_b32_e32 v191, 0xffff0000, v142
	v_pk_mul_f32 v[172:173], v[172:173], v[190:191]
	v_lshlrev_b32_e32 v190, 16, v143
	v_and_b32_e32 v191, 0xffff0000, v143
	v_pk_mul_f32 v[174:175], v[174:175], v[190:191]
	v_lshlrev_b32_e32 v190, 16, v144
	v_and_b32_e32 v191, 0xffff0000, v144
	v_pk_mul_f32 v[176:177], v[176:177], v[190:191]
	v_lshlrev_b32_e32 v190, 16, v145
	v_and_b32_e32 v191, 0xffff0000, v145
	v_pk_mul_f32 v[178:179], v[178:179], v[190:191]
	v_cvt_pk_bf16_f32 v186, v172, v173
	v_cvt_pk_bf16_f32 v187, v174, v175
	v_cvt_pk_bf16_f32 v188, v176, v177
	v_cvt_pk_bf16_f32 v189, v178, v179
	global_store_dwordx4 v[204:205], v[186:189], off
	s_nop 1
	v_lshl_add_u64 v[204:205], v[204:205], 0, s[38:39]
	ds_read_b128 v[172:175], v0 offset:16896
	ds_read_b128 v[176:179], v0 offset:16912
	s_waitcnt vmcnt(3) lgkmcnt(0)
	v_lshlrev_b32_e32 v190, 16, v146
	v_and_b32_e32 v191, 0xffff0000, v146
	v_pk_mul_f32 v[172:173], v[172:173], v[190:191]
	v_lshlrev_b32_e32 v190, 16, v147
	v_and_b32_e32 v191, 0xffff0000, v147
	v_pk_mul_f32 v[174:175], v[174:175], v[190:191]
	v_lshlrev_b32_e32 v190, 16, v148
	v_and_b32_e32 v191, 0xffff0000, v148
	v_pk_mul_f32 v[176:177], v[176:177], v[190:191]
	v_lshlrev_b32_e32 v190, 16, v149
	v_and_b32_e32 v191, 0xffff0000, v149
	v_pk_mul_f32 v[178:179], v[178:179], v[190:191]
	v_cvt_pk_bf16_f32 v186, v172, v173
	v_cvt_pk_bf16_f32 v187, v174, v175
	v_cvt_pk_bf16_f32 v188, v176, v177
	v_cvt_pk_bf16_f32 v189, v178, v179
	global_store_dwordx4 v[202:203], v[186:189], off
	s_nop 1
	v_lshl_add_u64 v[202:203], v[202:203], 0, s[38:39]
	ds_read_b128 v[172:175], v0 offset:25344
	ds_read_b128 v[176:179], v0 offset:25360
	s_waitcnt vmcnt(3) lgkmcnt(0)
	v_lshlrev_b32_e32 v190, 16, v150
	v_and_b32_e32 v191, 0xffff0000, v150
	v_pk_mul_f32 v[172:173], v[172:173], v[190:191]
	v_lshlrev_b32_e32 v190, 16, v151
	v_and_b32_e32 v191, 0xffff0000, v151
	v_pk_mul_f32 v[174:175], v[174:175], v[190:191]
	v_lshlrev_b32_e32 v190, 16, v152
	v_and_b32_e32 v191, 0xffff0000, v152
	v_pk_mul_f32 v[176:177], v[176:177], v[190:191]
	v_lshlrev_b32_e32 v190, 16, v153
	v_and_b32_e32 v191, 0xffff0000, v153
	v_pk_mul_f32 v[178:179], v[178:179], v[190:191]
	v_cvt_pk_bf16_f32 v186, v172, v173
	v_cvt_pk_bf16_f32 v187, v174, v175
	v_cvt_pk_bf16_f32 v188, v176, v177
	v_cvt_pk_bf16_f32 v189, v178, v179
	global_store_dwordx4 v[204:205], v[186:189], off
	s_nop 1
	v_lshl_add_u64 v[204:205], v[204:205], 0, s[38:39]
	global_load_dwordx4 v[138:141], v[194:195], off
	v_lshl_add_u64 v[194:195], v[194:195], 0, s[92:93]
	global_load_dwordx4 v[142:145], v[196:197], off
	v_lshl_add_u64 v[196:197], v[196:197], 0, s[92:93]
	global_load_dwordx4 v[146:149], v[194:195], off
	v_lshl_add_u64 v[194:195], v[194:195], 0, s[92:93]
	global_load_dwordx4 v[150:153], v[196:197], off
	v_lshl_add_u64 v[196:197], v[196:197], 0, s[92:93]
	ds_read_b128 v[172:175], v0 offset:33792
	ds_read_b128 v[176:179], v0 offset:33808
	s_waitcnt vmcnt(3) lgkmcnt(0)
	v_lshlrev_b32_e32 v190, 16, v138
	v_and_b32_e32 v191, 0xffff0000, v138
	v_pk_mul_f32 v[172:173], v[172:173], v[190:191]
	v_lshlrev_b32_e32 v190, 16, v139
	v_and_b32_e32 v191, 0xffff0000, v139
	v_pk_mul_f32 v[174:175], v[174:175], v[190:191]
	v_lshlrev_b32_e32 v190, 16, v140
	v_and_b32_e32 v191, 0xffff0000, v140
	v_pk_mul_f32 v[176:177], v[176:177], v[190:191]
	v_lshlrev_b32_e32 v190, 16, v141
	v_and_b32_e32 v191, 0xffff0000, v141
	v_pk_mul_f32 v[178:179], v[178:179], v[190:191]
	v_cvt_pk_bf16_f32 v186, v172, v173
	v_cvt_pk_bf16_f32 v187, v174, v175
	v_cvt_pk_bf16_f32 v188, v176, v177
	v_cvt_pk_bf16_f32 v189, v178, v179
	global_store_dwordx4 v[202:203], v[186:189], off
	s_nop 1
	v_lshl_add_u64 v[202:203], v[202:203], 0, s[38:39]
	ds_read_b128 v[172:175], v0 offset:42240
	ds_read_b128 v[176:179], v0 offset:42256
	s_waitcnt vmcnt(3) lgkmcnt(0)
; DI unsigned pk2(float a, float b) { f32x2 v = {a, b}; bf2_t r = __builtin_convertvector(v, bf2_t); return __builtin_bit_cast(unsigned, r); }
; DI float bf_lo(unsigned u) { return __uint_as_float(u << 16); }
; DI void gemm_mainloop_big(const bf16_t* __restrict__ A, int lda, const bf16_t* __restrict__ Bt, int ldb, int K, int m0, int n0,
;                           f32x16 (&acc)[4][2], char* smem) {
;     ...
;   const bf16_t* ap = A + (size_t)(m0 + (tid >> 3)) * lda + (tid & 7) * 8;
;   const bf16_t* bp = Bt + (size_t)(n0 + (tid >> 3)) * ldb + (tid & 7) * 8;
; #pragma unroll
;   for (int i = 0; i < 8; ++i) ra[i] = *(const u32x4*)(ap + (size_t)(32 * i) * lda);
; #pragma unroll
;   for (int i = 0; i < 4; ++i) rb[i] = *(const u32x4*)(bp + (size_t)(32 * i) * ldb);
;   __syncthreads();
; #pragma unroll
;   for (int i = 0; i < 8; ++i) *(u32x4*)&sa[(tid >> 3) + 32 * i][(tid & 7) * 8] = ra[i];
; #pragma unroll
;   for (int i = 0; i < 4; ++i) *(u32x4*)&sb[(tid >> 3) + 32 * i][(tid & 7) * 8] = rb[i];
;   __syncthreads();
; DI void gemm_up_pass_big(const bf16_t* Y, const bf16_t* W, const bf16_t* __restrict__ GBR, int gcol0, bf16_t* __restrict__ MG, bool first,
;                          int mt, int nt, char* smem) {
;     ...
;     const int r = tid >> 4, ch = tid & 15;
; #pragma unroll 2
;     for (int ps = 0; ps < 8; ++ps) {
;       const int row = ps * 16 + r;
;       const float4 a0 = *(const float4*)(st + row * 132 + ch * 8), a1 = *(const float4*)(st + row * 132 + ch * 8 + 4);
;       const size_t grow = (size_t)(m0 + h * 128 + row);
;       const u32x4 gv = *(const u32x4*)(GBR + grow * 2048 + gcol0 + n0 + ch * 8);
;       float v[8];
;       v[0] = bf_lo(gv.x) * a0.x; v[1] = bf_hi(gv.x) * a0.y; v[2] = bf_lo(gv.y) * a0.z; v[3] = bf_hi(gv.y) * a0.w;
;       v[4] = bf_lo(gv.z) * a1.x; v[5] = bf_hi(gv.z) * a1.y; v[6] = bf_lo(gv.w) * a1.z; v[7] = bf_hi(gv.w) * a1.w;
;       bf16_t* mp = MG + grow * 1024 + n0 + ch * 8;
;       if (!first) {
;         const u32x4 pv = *(const u32x4*)mp;
;         v[0] += bf_lo(pv.x); v[1] += bf_hi(pv.x); v[2] += bf_lo(pv.y); v[3] += bf_hi(pv.y);
;         v[4] += bf_lo(pv.z); v[5] += bf_hi(pv.z); v[6] += bf_lo(pv.w); v[7] += bf_hi(pv.w);
;       }
;       u32x4 ov; ov.x = pk2(v[0], v[1]); ov.y = pk2(v[2], v[3]); ov.z = pk2(v[4], v[5]); ov.w = pk2(v[6], v[7]);
;       *(u32x4*)mp = ov;
;     }
	v_lshlrev_b32_e32 v190, 16, v142
	v_and_b32_e32 v191, 0xffff0000, v142
	v_pk_mul_f32 v[172:173], v[172:173], v[190:191]
	v_lshlrev_b32_e32 v190, 16, v143
	v_and_b32_e32 v191, 0xffff0000, v143
	v_pk_mul_f32 v[174:175], v[174:175], v[190:191]
	v_lshlrev_b32_e32 v190, 16, v144
	v_and_b32_e32 v191, 0xffff0000, v144
	v_pk_mul_f32 v[176:177], v[176:177], v[190:191]
	v_lshlrev_b32_e32 v190, 16, v145
	v_and_b32_e32 v191, 0xffff0000, v145
	v_pk_mul_f32 v[178:179], v[178:179], v[190:191]
	v_cvt_pk_bf16_f32 v186, v172, v173
	v_cvt_pk_bf16_f32 v187, v174, v175
	v_cvt_pk_bf16_f32 v188, v176, v177
	v_cvt_pk_bf16_f32 v189, v178, v179
	global_store_dwordx4 v[204:205], v[186:189], off
	s_nop 1
	v_lshl_add_u64 v[204:205], v[204:205], 0, s[38:39]
	ds_read_b128 v[172:175], v0 offset:50688
	ds_read_b128 v[176:179], v0 offset:50704
	s_waitcnt vmcnt(3) lgkmcnt(0)
	v_lshlrev_b32_e32 v190, 16, v146
	v_and_b32_e32 v191, 0xffff0000, v146
	v_pk_mul_f32 v[172:173], v[172:173], v[190:191]
	v_lshlrev_b32_e32 v190, 16, v147
	v_and_b32_e32 v191, 0xffff0000, v147
	v_pk_mul_f32 v[174:175], v[174:175], v[190:191]
	v_lshlrev_b32_e32 v190, 16, v148
	v_and_b32_e32 v191, 0xffff0000, v148
	v_pk_mul_f32 v[176:177], v[176:177], v[190:191]
	v_lshlrev_b32_e32 v190, 16, v149
	v_and_b32_e32 v191, 0xffff0000, v149
	v_pk_mul_f32 v[178:179], v[178:179], v[190:191]
	v_cvt_pk_bf16_f32 v186, v172, v173
	v_cvt_pk_bf16_f32 v187, v174, v175
	v_cvt_pk_bf16_f32 v188, v176, v177
	v_cvt_pk_bf16_f32 v189, v178, v179
	global_store_dwordx4 v[202:203], v[186:189], off
	s_nop 1
	v_lshl_add_u64 v[202:203], v[202:203], 0, s[38:39]
	ds_read_b128 v[172:175], v0 offset:59136
	ds_read_b128 v[176:179], v0 offset:59152
	s_waitcnt vmcnt(3) lgkmcnt(0)
	v_lshlrev_b32_e32 v190, 16, v150
	v_and_b32_e32 v191, 0xffff0000, v150
	v_pk_mul_f32 v[172:173], v[172:173], v[190:191]
	v_lshlrev_b32_e32 v190, 16, v151
	v_and_b32_e32 v191, 0xffff0000, v151
	v_pk_mul_f32 v[174:175], v[174:175], v[190:191]
	v_lshlrev_b32_e32 v190, 16, v152
	v_and_b32_e32 v191, 0xffff0000, v152
	v_pk_mul_f32 v[176:177], v[176:177], v[190:191]
	v_lshlrev_b32_e32 v190, 16, v153
	v_and_b32_e32 v191, 0xffff0000, v153
	v_pk_mul_f32 v[178:179], v[178:179], v[190:191]
	v_cvt_pk_bf16_f32 v186, v172, v173
	v_cvt_pk_bf16_f32 v187, v174, v175
	v_cvt_pk_bf16_f32 v188, v176, v177
	v_cvt_pk_bf16_f32 v189, v178, v179
	global_store_dwordx4 v[204:205], v[186:189], off
	s_nop 1
	v_lshl_add_u64 v[204:205], v[204:205], 0, s[38:39]
	v_mov_b32_e32 v50, v216
	s_barrier
	v_readlane_b32 s42, v244, 40
	v_ashrrev_i32_e32 v51, 3, v50
	v_add_u32_e32 v2, s47, v51
	v_ashrrev_i32_e32 v3, 31, v2
	v_lshlrev_b64 v[2:3], 10, v[2:3]
	v_readlane_b32 s43, v244, 41
	v_lshlrev_b32_e32 v0, 4, v50
	v_and_b32_e32 v0, 0x70, v0
	v_lshl_add_u64 v[2:3], s[42:43], 0, v[2:3]
	v_lshl_add_u64 v[130:131], v[2:3], 0, v[0:1]
	s_mov_b32 s43, 0x8000
	v_add_co_u32_e32 v132, vcc, s43, v130
	s_mov_b32 s42, 0x18000
	s_nop 0
	v_addc_co_u32_e32 v133, vcc, 0, v131, vcc
	v_add_co_u32_e32 v134, vcc, s34, v130
	v_add_u32_e32 v2, s46, v51
	s_nop 0
	v_addc_co_u32_e32 v135, vcc, 0, v131, vcc
	v_add_co_u32_e32 v136, vcc, s42, v130
	s_mov_b32 s46, 0x28000
	s_nop 0
	v_addc_co_u32_e32 v137, vcc, 0, v131, vcc
	v_add_co_u32_e32 v138, vcc, s35, v130
	v_ashrrev_i32_e32 v3, 31, v2
	s_nop 0
	v_addc_co_u32_e32 v139, vcc, 0, v131, vcc
	v_add_co_u32_e32 v140, vcc, s46, v130
	v_lshlrev_b64 v[2:3], 10, v[2:3]
	s_nop 0
	v_addc_co_u32_e32 v141, vcc, 0, v131, vcc
	v_add_co_u32_e32 v142, vcc, s17, v130
	s_mov_b32 s46, 0x38000
	s_nop 0
	v_addc_co_u32_e32 v143, vcc, 0, v131, vcc
	v_lshl_add_u64 v[34:35], s[26:27], 0, v[2:3]
	v_add_co_u32_e32 v144, vcc, s46, v130
	v_lshl_add_u64 v[146:147], v[34:35], 0, v[0:1]
	s_nop 0
	v_addc_co_u32_e32 v145, vcc, 0, v131, vcc
	v_add_co_u32_e32 v150, vcc, s43, v146
	global_load_dwordx4 v[2:5], v[130:131], off
	global_load_dwordx4 v[6:9], v[132:133], off
	v_addc_co_u32_e32 v151, vcc, 0, v147, vcc
	v_add_co_u32_e32 v152, vcc, s34, v146
	global_load_dwordx4 v[10:13], v[134:135], off
	global_load_dwordx4 v[14:17], v[136:137], off
	v_addc_co_u32_e32 v153, vcc, 0, v147, vcc
	v_add_co_u32_e32 v154, vcc, s42, v146
	global_load_dwordx4 v[18:21], v[138:139], off
	global_load_dwordx4 v[22:25], v[140:141], off
	global_load_dwordx4 v[26:29], v[142:143], off
	global_load_dwordx4 v[30:33], v[144:145], off
	global_load_dwordx4 v[34:37], v[146:147], off
	global_load_dwordx4 v[38:41], v[150:151], off
	v_addc_co_u32_e32 v155, vcc, 0, v147, vcc
	global_load_dwordx4 v[42:45], v[152:153], off
	global_load_dwordx4 v[46:49], v[154:155], off
	s_movk_i32 s46, 0x90
	v_mad_u64_u32 v[148:149], s[42:43], v51, s46, v[0:1]
	v_and_b32_e32 v0, 31, v50
	s_barrier
	s_waitcnt vmcnt(11)
	ds_write_b128 v148, v[2:5]
	s_waitcnt vmcnt(3)
	ds_write_b128 v148, v[34:37] offset:36864
	ds_write_b128 v148, v[6:9] offset:4608
	ds_write_b128 v148, v[10:13] offset:9216
	ds_write_b128 v148, v[14:17] offset:13824
	ds_write_b128 v148, v[18:21] offset:18432
	ds_write_b128 v148, v[22:25] offset:23040
	ds_write_b128 v148, v[26:29] offset:27648
	ds_write_b128 v148, v[30:33] offset:32256
	s_waitcnt vmcnt(2)
	ds_write_b128 v148, v[38:41] offset:41472
	s_waitcnt vmcnt(1)
	ds_write_b128 v148, v[42:45] offset:46080
	s_waitcnt vmcnt(0)
	ds_write_b128 v148, v[46:49] offset:50688
	v_mul_u32_u24_e32 v6, 0x90, v0
	v_and_b32_e32 v0, 0xfffff80, v50
	v_lshrrev_b32_e32 v2, 1, v50
	v_mul_lo_u32 v0, v0, s46
	v_and_b32_e32 v7, 16, v2
	v_add3_u32 v0, v6, v0, v7
	s_waitcnt lgkmcnt(0)
	s_barrier
; #define MFMA32(a, b, c) __builtin_amdgcn_mfma_f32_32x32x16_bf16((a), (b), (c), 0, 0, 0)
; DI void gemm_mainloop_big(const bf16_t* __restrict__ A, int lda, const bf16_t* __restrict__ Bt, int ldb, int K, int m0, int n0,
;                           f32x16 (&acc)[4][2], char* smem) {
;     ...
;   for (int kt = 0; kt < nk; ++kt) {
;     if (kt + 1 < nk) {
; #pragma unroll
;       for (int i = 0; i < 8; ++i) ra[i] = *(const u32x4*)(ap + (size_t)(32 * i) * lda + (kt + 1) * 64);
; #pragma unroll
;       for (int i = 0; i < 4; ++i) rb[i] = *(const u32x4*)(bp + (size_t)(32 * i) * ldb + (kt + 1) * 64);
;     }
; #pragma unroll
;     for (int ks = 0; ks < 4; ++ks) {
;       bf16x8 af[4], bfr[2];
; #pragma unroll
;       for (int f = 0; f < 4; ++f) af[f] = *(const bf16x8*)&sa[wm * 128 + f * 32 + r][ks * 16 + half * 8];
; #pragma unroll
;       for (int f = 0; f < 2; ++f) bfr[f] = *(const bf16x8*)&sb[wn * 64 + f * 32 + r][ks * 16 + half * 8];
; #pragma unroll
;       for (int mf = 0; mf < 4; ++mf)
; #pragma unroll
;         for (int nf = 0; nf < 2; ++nf) acc[mf][nf] = MFMA32(af[mf], bfr[nf], acc[mf][nf]);
;     }
;     __syncthreads();
;     if (kt + 1 < nk) {
; #pragma unroll
;       for (int i = 0; i < 8; ++i) *(u32x4*)&sa[(tid >> 3) + 32 * i][(tid & 7) * 8] = ra[i];
; #pragma unroll
;       for (int i = 0; i < 4; ++i) *(u32x4*)&sb[(tid >> 3) + 32 * i][(tid & 7) * 8] = rb[i];
;     }
;     __syncthreads();
	ds_read_b128 v[2:5], v0
	v_and_b32_e32 v8, 64, v50
	v_mul_u32_u24_e32 v8, 0x90, v8
	v_add3_u32 v149, v6, v8, v7
	ds_read_b128 v[6:9], v149 offset:36864
	ds_read_b128 v[156:159], v0 offset:32
	ds_read_b128 v[160:163], v149 offset:36896
	ds_read_b128 v[18:21], v149 offset:41472
	ds_read_b128 v[164:167], v149 offset:41504
	s_waitcnt lgkmcnt(4)
	v_mfma_f32_32x32x16_bf16 v[98:113], v[2:5], v[6:9], 0
	s_waitcnt lgkmcnt(1)
	v_mfma_f32_32x32x16_bf16 v[114:129], v[2:5], v[18:21], 0
	ds_read_b128 v[2:5], v0 offset:4608
	ds_read_b128 v[168:171], v0 offset:4640
	s_waitcnt lgkmcnt(1)
	v_mfma_f32_32x32x16_bf16 v[66:81], v[2:5], v[6:9], 0
	v_mfma_f32_32x32x16_bf16 v[82:97], v[2:5], v[18:21], 0
	ds_read_b128 v[2:5], v0 offset:9216
	ds_read_b128 v[172:175], v0 offset:9248
	ds_read_b128 v[22:25], v0 offset:13824
	ds_read_b128 v[176:179], v0 offset:13856
	s_waitcnt lgkmcnt(3)
	v_mfma_f32_32x32x16_bf16 v[34:49], v[2:5], v[6:9], 0
	v_mfma_f32_32x32x16_bf16 v[50:65], v[2:5], v[18:21], 0
	s_waitcnt lgkmcnt(1)
	v_mfma_f32_32x32x16_bf16 v[2:17], v[22:25], v[6:9], 0
	v_mfma_f32_32x32x16_bf16 v[18:33], v[22:25], v[18:21], 0
	v_mfma_f32_32x32x16_bf16 v[98:113], v[156:159], v[160:163], v[98:113]
	v_mfma_f32_32x32x16_bf16 v[114:129], v[156:159], v[164:167], v[114:129]
	v_mfma_f32_32x32x16_bf16 v[66:81], v[168:171], v[160:163], v[66:81]
	v_mfma_f32_32x32x16_bf16 v[82:97], v[168:171], v[164:167], v[82:97]
	v_mfma_f32_32x32x16_bf16 v[34:49], v[172:175], v[160:163], v[34:49]
	v_mfma_f32_32x32x16_bf16 v[50:65], v[172:175], v[164:167], v[50:65]
	s_waitcnt lgkmcnt(0)
	v_mfma_f32_32x32x16_bf16 v[2:17], v[176:179], v[160:163], v[2:17]
	v_mfma_f32_32x32x16_bf16 v[18:33], v[176:179], v[164:167], v[18:33]
	ds_read_b128 v[156:159], v0 offset:64
	ds_read_b128 v[160:163], v149 offset:36928
	ds_read_b128 v[164:167], v0 offset:96
	ds_read_b128 v[168:171], v149 offset:36960
	ds_read_b128 v[172:175], v149 offset:41536
	ds_read_b128 v[176:179], v149 offset:41568
	s_waitcnt lgkmcnt(4)
	v_mfma_f32_32x32x16_bf16 v[98:113], v[156:159], v[160:163], v[98:113]
	s_waitcnt lgkmcnt(1)
	v_mfma_f32_32x32x16_bf16 v[114:129], v[156:159], v[172:175], v[114:129]
	ds_read_b128 v[156:159], v0 offset:4672
	ds_read_b128 v[186:189], v0 offset:4704
	s_waitcnt lgkmcnt(1)
	v_mfma_f32_32x32x16_bf16 v[66:81], v[156:159], v[160:163], v[66:81]
	v_mfma_f32_32x32x16_bf16 v[82:97], v[156:159], v[172:175], v[82:97]
	ds_read_b128 v[156:159], v0 offset:9280
	ds_read_b128 v[190:193], v0 offset:9312
	s_waitcnt lgkmcnt(1)
	v_mfma_f32_32x32x16_bf16 v[34:49], v[156:159], v[160:163], v[34:49]
	v_mfma_f32_32x32x16_bf16 v[50:65], v[156:159], v[172:175], v[50:65]
	ds_read_b128 v[156:159], v0 offset:13888
	ds_read_b128 v[194:197], v0 offset:13920
	s_waitcnt lgkmcnt(1)
	v_mfma_f32_32x32x16_bf16 v[2:17], v[156:159], v[160:163], v[2:17]
	v_mfma_f32_32x32x16_bf16 v[18:33], v[156:159], v[172:175], v[18:33]
	global_load_dwordx4 v[156:159], v[130:131], off offset:128
	global_load_dwordx4 v[160:163], v[132:133], off offset:128
	v_mfma_f32_32x32x16_bf16 v[98:113], v[164:167], v[168:171], v[98:113]
	v_mfma_f32_32x32x16_bf16 v[114:129], v[164:167], v[176:179], v[114:129]
	v_mfma_f32_32x32x16_bf16 v[66:81], v[186:189], v[168:171], v[66:81]
	v_mfma_f32_32x32x16_bf16 v[82:97], v[186:189], v[176:179], v[82:97]
	v_mfma_f32_32x32x16_bf16 v[34:49], v[190:193], v[168:171], v[34:49]
	v_mfma_f32_32x32x16_bf16 v[50:65], v[190:193], v[176:179], v[50:65]
	global_load_dwordx4 v[164:167], v[134:135], off offset:128
	global_load_dwordx4 v[172:175], v[136:137], off offset:128
	global_load_dwordx4 v[186:189], v[138:139], off offset:128
	global_load_dwordx4 v[190:193], v[140:141], off offset:128
	global_load_dwordx4 v[198:201], v[142:143], off offset:128
	global_load_dwordx4 v[202:205], v[144:145], off offset:128
	global_load_dwordx4 v[206:209], v[146:147], off offset:128
	global_load_dwordx4 v[210:213], v[150:151], off offset:128
	s_waitcnt lgkmcnt(0)
	v_mfma_f32_32x32x16_bf16 v[2:17], v[194:197], v[168:171], v[2:17]
	global_load_dwordx4 v[168:171], v[152:153], off offset:128
	global_load_dwordx4 v[236:239], v[154:155], off offset:128
	s_barrier
	s_waitcnt vmcnt(11)
	ds_write_b128 v148, v[156:159]
	s_waitcnt vmcnt(10)
	ds_write_b128 v148, v[160:163] offset:4608
	s_waitcnt vmcnt(9)
	ds_write_b128 v148, v[164:167] offset:9216
	s_waitcnt vmcnt(8)
	ds_write_b128 v148, v[172:175] offset:13824
	s_waitcnt vmcnt(7)
	ds_write_b128 v148, v[186:189] offset:18432
	s_waitcnt vmcnt(6)
	ds_write_b128 v148, v[190:193] offset:23040
	s_waitcnt vmcnt(5)
	ds_write_b128 v148, v[198:201] offset:27648
	s_waitcnt vmcnt(4)
	ds_write_b128 v148, v[202:205] offset:32256
	s_waitcnt vmcnt(3)
	ds_write_b128 v148, v[206:209] offset:36864
	s_waitcnt vmcnt(2)
	ds_write_b128 v148, v[210:213] offset:41472
	s_waitcnt vmcnt(1)
	ds_write_b128 v148, v[168:171] offset:46080
	s_waitcnt vmcnt(0)
	ds_write_b128 v148, v[236:239] offset:50688
	v_mfma_f32_32x32x16_bf16 v[18:33], v[194:197], v[176:179], v[18:33]
	s_waitcnt lgkmcnt(0)
	s_barrier
; #define MFMA32(a, b, c) __builtin_amdgcn_mfma_f32_32x32x16_bf16((a), (b), (c), 0, 0, 0)
; DI void gemm_mainloop_big(const bf16_t* __restrict__ A, int lda, const bf16_t* __restrict__ Bt, int ldb, int K, int m0, int n0,
;                           f32x16 (&acc)[4][2], char* smem) {
;     ...
;   for (int kt = 0; kt < nk; ++kt) {
;     if (kt + 1 < nk) {
; #pragma unroll
;       for (int i = 0; i < 8; ++i) ra[i] = *(const u32x4*)(ap + (size_t)(32 * i) * lda + (kt + 1) * 64);
; #pragma unroll
;       for (int i = 0; i < 4; ++i) rb[i] = *(const u32x4*)(bp + (size_t)(32 * i) * ldb + (kt + 1) * 64);
;     }
; #pragma unroll
;     for (int ks = 0; ks < 4; ++ks) {
;       bf16x8 af[4], bfr[2];
; #pragma unroll
;       for (int f = 0; f < 4; ++f) af[f] = *(const bf16x8*)&sa[wm * 128 + f * 32 + r][ks * 16 + half * 8];
; #pragma unroll
;       for (int f = 0; f < 2; ++f) bfr[f] = *(const bf16x8*)&sb[wn * 64 + f * 32 + r][ks * 16 + half * 8];
; #pragma unroll
;       for (int mf = 0; mf < 4; ++mf)
; #pragma unroll
;         for (int nf = 0; nf < 2; ++nf) acc[mf][nf] = MFMA32(af[mf], bfr[nf], acc[mf][nf]);
;     }
;     __syncthreads();
;     if (kt + 1 < nk) {
; #pragma unroll
;       for (int i = 0; i < 8; ++i) *(u32x4*)&sa[(tid >> 3) + 32 * i][(tid & 7) * 8] = ra[i];
; #pragma unroll
;       for (int i = 0; i < 4; ++i) *(u32x4*)&sb[(tid >> 3) + 32 * i][(tid & 7) * 8] = rb[i];
;     }
;     __syncthreads();
	ds_read_b128 v[156:159], v0
	ds_read_b128 v[160:163], v149 offset:36864
	ds_read_b128 v[164:167], v0 offset:32
	ds_read_b128 v[168:171], v149 offset:36896
	ds_read_b128 v[172:175], v149 offset:41472
	ds_read_b128 v[176:179], v149 offset:41504
	s_waitcnt lgkmcnt(4)
	v_mfma_f32_32x32x16_bf16 v[98:113], v[156:159], v[160:163], v[98:113]
	s_waitcnt lgkmcnt(1)
	v_mfma_f32_32x32x16_bf16 v[114:129], v[156:159], v[172:175], v[114:129]
	ds_read_b128 v[156:159], v0 offset:4608
	ds_read_b128 v[186:189], v0 offset:4640
	s_waitcnt lgkmcnt(1)
	v_mfma_f32_32x32x16_bf16 v[66:81], v[156:159], v[160:163], v[66:81]
	v_mfma_f32_32x32x16_bf16 v[82:97], v[156:159], v[172:175], v[82:97]
	ds_read_b128 v[156:159], v0 offset:9216
	ds_read_b128 v[190:193], v0 offset:9248
	s_waitcnt lgkmcnt(1)
	v_mfma_f32_32x32x16_bf16 v[34:49], v[156:159], v[160:163], v[34:49]
	v_mfma_f32_32x32x16_bf16 v[50:65], v[156:159], v[172:175], v[50:65]
	ds_read_b128 v[156:159], v0 offset:13824
	ds_read_b128 v[194:197], v0 offset:13856
	s_waitcnt lgkmcnt(1)
	v_mfma_f32_32x32x16_bf16 v[2:17], v[156:159], v[160:163], v[2:17]
	v_mfma_f32_32x32x16_bf16 v[18:33], v[156:159], v[172:175], v[18:33]
	v_mfma_f32_32x32x16_bf16 v[98:113], v[164:167], v[168:171], v[98:113]
	v_mfma_f32_32x32x16_bf16 v[114:129], v[164:167], v[176:179], v[114:129]
	v_mfma_f32_32x32x16_bf16 v[66:81], v[186:189], v[168:171], v[66:81]
	v_mfma_f32_32x32x16_bf16 v[82:97], v[186:189], v[176:179], v[82:97]
	v_mfma_f32_32x32x16_bf16 v[34:49], v[190:193], v[168:171], v[34:49]
	v_mfma_f32_32x32x16_bf16 v[50:65], v[190:193], v[176:179], v[50:65]
	s_waitcnt lgkmcnt(0)
	v_mfma_f32_32x32x16_bf16 v[2:17], v[194:197], v[168:171], v[2:17]
	ds_read_b128 v[156:159], v0 offset:64
	ds_read_b128 v[160:163], v149 offset:36928
	ds_read_b128 v[164:167], v0 offset:96
	ds_read_b128 v[168:171], v149 offset:36960
	v_mfma_f32_32x32x16_bf16 v[18:33], v[194:197], v[176:179], v[18:33]
	ds_read_b128 v[172:175], v149 offset:41536
	ds_read_b128 v[176:179], v149 offset:41568
	s_waitcnt lgkmcnt(4)
	v_mfma_f32_32x32x16_bf16 v[98:113], v[156:159], v[160:163], v[98:113]
	s_waitcnt lgkmcnt(1)
	v_mfma_f32_32x32x16_bf16 v[114:129], v[156:159], v[172:175], v[114:129]
	ds_read_b128 v[156:159], v0 offset:4672
	ds_read_b128 v[186:189], v0 offset:4704
	s_waitcnt lgkmcnt(1)
	v_mfma_f32_32x32x16_bf16 v[66:81], v[156:159], v[160:163], v[66:81]
	v_mfma_f32_32x32x16_bf16 v[82:97], v[156:159], v[172:175], v[82:97]
	ds_read_b128 v[156:159], v0 offset:9280
	ds_read_b128 v[190:193], v0 offset:9312
	s_waitcnt lgkmcnt(1)
	v_mfma_f32_32x32x16_bf16 v[34:49], v[156:159], v[160:163], v[34:49]
	v_mfma_f32_32x32x16_bf16 v[50:65], v[156:159], v[172:175], v[50:65]
	ds_read_b128 v[156:159], v0 offset:13888
	ds_read_b128 v[194:197], v0 offset:13920
	s_waitcnt lgkmcnt(1)
	v_mfma_f32_32x32x16_bf16 v[2:17], v[156:159], v[160:163], v[2:17]
	v_mfma_f32_32x32x16_bf16 v[18:33], v[156:159], v[172:175], v[18:33]
	global_load_dwordx4 v[156:159], v[130:131], off offset:256
	global_load_dwordx4 v[160:163], v[132:133], off offset:256
	v_mfma_f32_32x32x16_bf16 v[98:113], v[164:167], v[168:171], v[98:113]
	v_mfma_f32_32x32x16_bf16 v[114:129], v[164:167], v[176:179], v[114:129]
	v_mfma_f32_32x32x16_bf16 v[66:81], v[186:189], v[168:171], v[66:81]
	v_mfma_f32_32x32x16_bf16 v[82:97], v[186:189], v[176:179], v[82:97]
	v_mfma_f32_32x32x16_bf16 v[34:49], v[190:193], v[168:171], v[34:49]
	v_mfma_f32_32x32x16_bf16 v[50:65], v[190:193], v[176:179], v[50:65]
	global_load_dwordx4 v[164:167], v[134:135], off offset:256
	global_load_dwordx4 v[172:175], v[136:137], off offset:256
	global_load_dwordx4 v[186:189], v[138:139], off offset:256
	global_load_dwordx4 v[190:193], v[140:141], off offset:256
	global_load_dwordx4 v[198:201], v[142:143], off offset:256
	global_load_dwordx4 v[202:205], v[144:145], off offset:256
	global_load_dwordx4 v[206:209], v[146:147], off offset:256
	global_load_dwordx4 v[210:213], v[150:151], off offset:256
	s_waitcnt lgkmcnt(0)
	v_mfma_f32_32x32x16_bf16 v[2:17], v[194:197], v[168:171], v[2:17]
	global_load_dwordx4 v[168:171], v[152:153], off offset:256
	global_load_dwordx4 v[236:239], v[154:155], off offset:256
	s_barrier
	s_waitcnt vmcnt(11)
	ds_write_b128 v148, v[156:159]
	s_waitcnt vmcnt(10)
	ds_write_b128 v148, v[160:163] offset:4608
	s_waitcnt vmcnt(9)
	ds_write_b128 v148, v[164:167] offset:9216
	s_waitcnt vmcnt(8)
	ds_write_b128 v148, v[172:175] offset:13824
	s_waitcnt vmcnt(7)
	ds_write_b128 v148, v[186:189] offset:18432
	s_waitcnt vmcnt(6)
	ds_write_b128 v148, v[190:193] offset:23040
	s_waitcnt vmcnt(5)
	ds_write_b128 v148, v[198:201] offset:27648
	s_waitcnt vmcnt(4)
	ds_write_b128 v148, v[202:205] offset:32256
	s_waitcnt vmcnt(3)
	ds_write_b128 v148, v[206:209] offset:36864
	s_waitcnt vmcnt(2)
	ds_write_b128 v148, v[210:213] offset:41472
	s_waitcnt vmcnt(1)
	ds_write_b128 v148, v[168:171] offset:46080
	s_waitcnt vmcnt(0)
	ds_write_b128 v148, v[236:239] offset:50688
	v_mfma_f32_32x32x16_bf16 v[18:33], v[194:197], v[176:179], v[18:33]
	s_waitcnt lgkmcnt(0)
	s_barrier
; #define MFMA32(a, b, c) __builtin_amdgcn_mfma_f32_32x32x16_bf16((a), (b), (c), 0, 0, 0)
; DI void gemm_mainloop_big(const bf16_t* __restrict__ A, int lda, const bf16_t* __restrict__ Bt, int ldb, int K, int m0, int n0,
;                           f32x16 (&acc)[4][2], char* smem) {
;     ...
;   for (int kt = 0; kt < nk; ++kt) {
;     if (kt + 1 < nk) {
; #pragma unroll
;       for (int i = 0; i < 8; ++i) ra[i] = *(const u32x4*)(ap + (size_t)(32 * i) * lda + (kt + 1) * 64);
; #pragma unroll
;       for (int i = 0; i < 4; ++i) rb[i] = *(const u32x4*)(bp + (size_t)(32 * i) * ldb + (kt + 1) * 64);
;     }
; #pragma unroll
;     for (int ks = 0; ks < 4; ++ks) {
;       bf16x8 af[4], bfr[2];
; #pragma unroll
;       for (int f = 0; f < 4; ++f) af[f] = *(const bf16x8*)&sa[wm * 128 + f * 32 + r][ks * 16 + half * 8];
; #pragma unroll
;       for (int f = 0; f < 2; ++f) bfr[f] = *(const bf16x8*)&sb[wn * 64 + f * 32 + r][ks * 16 + half * 8];
; #pragma unroll
;       for (int mf = 0; mf < 4; ++mf)
; #pragma unroll
;         for (int nf = 0; nf < 2; ++nf) acc[mf][nf] = MFMA32(af[mf], bfr[nf], acc[mf][nf]);
;     }
;     __syncthreads();
;     if (kt + 1 < nk) {
; #pragma unroll
;       for (int i = 0; i < 8; ++i) *(u32x4*)&sa[(tid >> 3) + 32 * i][(tid & 7) * 8] = ra[i];
; #pragma unroll
;       for (int i = 0; i < 4; ++i) *(u32x4*)&sb[(tid >> 3) + 32 * i][(tid & 7) * 8] = rb[i];
;     }
;     __syncthreads();
	ds_read_b128 v[156:159], v0
	ds_read_b128 v[160:163], v149 offset:36864
	ds_read_b128 v[164:167], v0 offset:32
	ds_read_b128 v[168:171], v149 offset:36896
	ds_read_b128 v[172:175], v149 offset:41472
	ds_read_b128 v[176:179], v149 offset:41504
	s_waitcnt lgkmcnt(4)
	v_mfma_f32_32x32x16_bf16 v[98:113], v[156:159], v[160:163], v[98:113]
	s_waitcnt lgkmcnt(1)
	v_mfma_f32_32x32x16_bf16 v[114:129], v[156:159], v[172:175], v[114:129]
	ds_read_b128 v[156:159], v0 offset:4608
	ds_read_b128 v[186:189], v0 offset:4640
	s_waitcnt lgkmcnt(1)
	v_mfma_f32_32x32x16_bf16 v[66:81], v[156:159], v[160:163], v[66:81]
	v_mfma_f32_32x32x16_bf16 v[82:97], v[156:159], v[172:175], v[82:97]
	ds_read_b128 v[156:159], v0 offset:9216
	ds_read_b128 v[190:193], v0 offset:9248
	s_waitcnt lgkmcnt(1)
	v_mfma_f32_32x32x16_bf16 v[34:49], v[156:159], v[160:163], v[34:49]
	v_mfma_f32_32x32x16_bf16 v[50:65], v[156:159], v[172:175], v[50:65]
	ds_read_b128 v[156:159], v0 offset:13824
	ds_read_b128 v[194:197], v0 offset:13856
	s_waitcnt lgkmcnt(1)
	v_mfma_f32_32x32x16_bf16 v[2:17], v[156:159], v[160:163], v[2:17]
	v_mfma_f32_32x32x16_bf16 v[18:33], v[156:159], v[172:175], v[18:33]
	v_mfma_f32_32x32x16_bf16 v[98:113], v[164:167], v[168:171], v[98:113]
	v_mfma_f32_32x32x16_bf16 v[114:129], v[164:167], v[176:179], v[114:129]
	v_mfma_f32_32x32x16_bf16 v[66:81], v[186:189], v[168:171], v[66:81]
	v_mfma_f32_32x32x16_bf16 v[82:97], v[186:189], v[176:179], v[82:97]
	v_mfma_f32_32x32x16_bf16 v[34:49], v[190:193], v[168:171], v[34:49]
	v_mfma_f32_32x32x16_bf16 v[50:65], v[190:193], v[176:179], v[50:65]
	s_waitcnt lgkmcnt(0)
	v_mfma_f32_32x32x16_bf16 v[2:17], v[194:197], v[168:171], v[2:17]
	ds_read_b128 v[156:159], v0 offset:64
	ds_read_b128 v[160:163], v149 offset:36928
	ds_read_b128 v[164:167], v0 offset:96
	ds_read_b128 v[168:171], v149 offset:36960
	v_mfma_f32_32x32x16_bf16 v[18:33], v[194:197], v[176:179], v[18:33]
	ds_read_b128 v[172:175], v149 offset:41536
	ds_read_b128 v[176:179], v149 offset:41568
	s_waitcnt lgkmcnt(4)
	v_mfma_f32_32x32x16_bf16 v[98:113], v[156:159], v[160:163], v[98:113]
	s_waitcnt lgkmcnt(1)
	v_mfma_f32_32x32x16_bf16 v[114:129], v[156:159], v[172:175], v[114:129]
	ds_read_b128 v[156:159], v0 offset:4672
	ds_read_b128 v[186:189], v0 offset:4704
	s_waitcnt lgkmcnt(1)
	v_mfma_f32_32x32x16_bf16 v[66:81], v[156:159], v[160:163], v[66:81]
	v_mfma_f32_32x32x16_bf16 v[82:97], v[156:159], v[172:175], v[82:97]
	ds_read_b128 v[156:159], v0 offset:9280
	ds_read_b128 v[190:193], v0 offset:9312
	s_waitcnt lgkmcnt(1)
	v_mfma_f32_32x32x16_bf16 v[34:49], v[156:159], v[160:163], v[34:49]
	v_mfma_f32_32x32x16_bf16 v[50:65], v[156:159], v[172:175], v[50:65]
	ds_read_b128 v[156:159], v0 offset:13888
	ds_read_b128 v[194:197], v0 offset:13920
	s_waitcnt lgkmcnt(1)
	v_mfma_f32_32x32x16_bf16 v[2:17], v[156:159], v[160:163], v[2:17]
	v_mfma_f32_32x32x16_bf16 v[18:33], v[156:159], v[172:175], v[18:33]
	global_load_dwordx4 v[156:159], v[130:131], off offset:384
	global_load_dwordx4 v[160:163], v[132:133], off offset:384
	v_mfma_f32_32x32x16_bf16 v[98:113], v[164:167], v[168:171], v[98:113]
	v_mfma_f32_32x32x16_bf16 v[114:129], v[164:167], v[176:179], v[114:129]
	v_mfma_f32_32x32x16_bf16 v[66:81], v[186:189], v[168:171], v[66:81]
	v_mfma_f32_32x32x16_bf16 v[82:97], v[186:189], v[176:179], v[82:97]
	v_mfma_f32_32x32x16_bf16 v[34:49], v[190:193], v[168:171], v[34:49]
	v_mfma_f32_32x32x16_bf16 v[50:65], v[190:193], v[176:179], v[50:65]
	global_load_dwordx4 v[164:167], v[134:135], off offset:384
	global_load_dwordx4 v[172:175], v[136:137], off offset:384
	global_load_dwordx4 v[186:189], v[138:139], off offset:384
	global_load_dwordx4 v[190:193], v[140:141], off offset:384
	global_load_dwordx4 v[198:201], v[142:143], off offset:384
	global_load_dwordx4 v[202:205], v[144:145], off offset:384
	global_load_dwordx4 v[206:209], v[146:147], off offset:384
	global_load_dwordx4 v[210:213], v[150:151], off offset:384
	s_waitcnt lgkmcnt(0)
	v_mfma_f32_32x32x16_bf16 v[2:17], v[194:197], v[168:171], v[2:17]
	global_load_dwordx4 v[168:171], v[152:153], off offset:384
	global_load_dwordx4 v[236:239], v[154:155], off offset:384
	s_barrier
	s_waitcnt vmcnt(11)
	ds_write_b128 v148, v[156:159]
	s_waitcnt vmcnt(10)
	ds_write_b128 v148, v[160:163] offset:4608
	s_waitcnt vmcnt(9)
	ds_write_b128 v148, v[164:167] offset:9216
	s_waitcnt vmcnt(8)
	ds_write_b128 v148, v[172:175] offset:13824
	s_waitcnt vmcnt(7)
	ds_write_b128 v148, v[186:189] offset:18432
	s_waitcnt vmcnt(6)
	ds_write_b128 v148, v[190:193] offset:23040
	s_waitcnt vmcnt(5)
	ds_write_b128 v148, v[198:201] offset:27648
	s_waitcnt vmcnt(4)
	ds_write_b128 v148, v[202:205] offset:32256
	s_waitcnt vmcnt(3)
	ds_write_b128 v148, v[206:209] offset:36864
	s_waitcnt vmcnt(2)
	ds_write_b128 v148, v[210:213] offset:41472
	s_waitcnt vmcnt(1)
	ds_write_b128 v148, v[168:171] offset:46080
	s_waitcnt vmcnt(0)
	ds_write_b128 v148, v[236:239] offset:50688
	v_mfma_f32_32x32x16_bf16 v[18:33], v[194:197], v[176:179], v[18:33]
	s_waitcnt lgkmcnt(0)
	s_barrier
; #define MFMA32(a, b, c) __builtin_amdgcn_mfma_f32_32x32x16_bf16((a), (b), (c), 0, 0, 0)
; DI void gemm_mainloop_big(const bf16_t* __restrict__ A, int lda, const bf16_t* __restrict__ Bt, int ldb, int K, int m0, int n0,
;                           f32x16 (&acc)[4][2], char* smem) {
;     ...
;   for (int kt = 0; kt < nk; ++kt) {
;     if (kt + 1 < nk) {
; #pragma unroll
;       for (int i = 0; i < 8; ++i) ra[i] = *(const u32x4*)(ap + (size_t)(32 * i) * lda + (kt + 1) * 64);
; #pragma unroll
;       for (int i = 0; i < 4; ++i) rb[i] = *(const u32x4*)(bp + (size_t)(32 * i) * ldb + (kt + 1) * 64);
;     }
; #pragma unroll
;     for (int ks = 0; ks < 4; ++ks) {
;       bf16x8 af[4], bfr[2];
; #pragma unroll
;       for (int f = 0; f < 4; ++f) af[f] = *(const bf16x8*)&sa[wm * 128 + f * 32 + r][ks * 16 + half * 8];
; #pragma unroll
;       for (int f = 0; f < 2; ++f) bfr[f] = *(const bf16x8*)&sb[wn * 64 + f * 32 + r][ks * 16 + half * 8];
; #pragma unroll
;       for (int mf = 0; mf < 4; ++mf)
; #pragma unroll
;         for (int nf = 0; nf < 2; ++nf) acc[mf][nf] = MFMA32(af[mf], bfr[nf], acc[mf][nf]);
;     }
;     __syncthreads();
;     if (kt + 1 < nk) {
; #pragma unroll
;       for (int i = 0; i < 8; ++i) *(u32x4*)&sa[(tid >> 3) + 32 * i][(tid & 7) * 8] = ra[i];
; #pragma unroll
;       for (int i = 0; i < 4; ++i) *(u32x4*)&sb[(tid >> 3) + 32 * i][(tid & 7) * 8] = rb[i];
;     }
;     __syncthreads();
	ds_read_b128 v[156:159], v0
	ds_read_b128 v[160:163], v149 offset:36864
	ds_read_b128 v[164:167], v0 offset:32
	ds_read_b128 v[168:171], v149 offset:36896
	ds_read_b128 v[172:175], v149 offset:41472
	ds_read_b128 v[176:179], v149 offset:41504
	s_waitcnt lgkmcnt(4)
	v_mfma_f32_32x32x16_bf16 v[98:113], v[156:159], v[160:163], v[98:113]
	s_waitcnt lgkmcnt(1)
	v_mfma_f32_32x32x16_bf16 v[114:129], v[156:159], v[172:175], v[114:129]
	ds_read_b128 v[156:159], v0 offset:4608
	ds_read_b128 v[186:189], v0 offset:4640
	s_waitcnt lgkmcnt(1)
	v_mfma_f32_32x32x16_bf16 v[66:81], v[156:159], v[160:163], v[66:81]
	v_mfma_f32_32x32x16_bf16 v[82:97], v[156:159], v[172:175], v[82:97]
	ds_read_b128 v[156:159], v0 offset:9216
	ds_read_b128 v[190:193], v0 offset:9248
	s_waitcnt lgkmcnt(1)
	v_mfma_f32_32x32x16_bf16 v[34:49], v[156:159], v[160:163], v[34:49]
	v_mfma_f32_32x32x16_bf16 v[50:65], v[156:159], v[172:175], v[50:65]
	ds_read_b128 v[156:159], v0 offset:13824
	ds_read_b128 v[194:197], v0 offset:13856
	s_waitcnt lgkmcnt(1)
	v_mfma_f32_32x32x16_bf16 v[2:17], v[156:159], v[160:163], v[2:17]
	v_mfma_f32_32x32x16_bf16 v[18:33], v[156:159], v[172:175], v[18:33]
	v_mfma_f32_32x32x16_bf16 v[98:113], v[164:167], v[168:171], v[98:113]
	v_mfma_f32_32x32x16_bf16 v[114:129], v[164:167], v[176:179], v[114:129]
	v_mfma_f32_32x32x16_bf16 v[66:81], v[186:189], v[168:171], v[66:81]
	v_mfma_f32_32x32x16_bf16 v[82:97], v[186:189], v[176:179], v[82:97]
	v_mfma_f32_32x32x16_bf16 v[34:49], v[190:193], v[168:171], v[34:49]
	v_mfma_f32_32x32x16_bf16 v[50:65], v[190:193], v[176:179], v[50:65]
	s_waitcnt lgkmcnt(0)
	v_mfma_f32_32x32x16_bf16 v[2:17], v[194:197], v[168:171], v[2:17]
	ds_read_b128 v[156:159], v0 offset:64
	ds_read_b128 v[160:163], v149 offset:36928
	ds_read_b128 v[164:167], v0 offset:96
	ds_read_b128 v[168:171], v149 offset:36960
	v_mfma_f32_32x32x16_bf16 v[18:33], v[194:197], v[176:179], v[18:33]
	ds_read_b128 v[172:175], v149 offset:41536
	ds_read_b128 v[176:179], v149 offset:41568
	s_waitcnt lgkmcnt(4)
	v_mfma_f32_32x32x16_bf16 v[98:113], v[156:159], v[160:163], v[98:113]
	s_waitcnt lgkmcnt(1)
	v_mfma_f32_32x32x16_bf16 v[114:129], v[156:159], v[172:175], v[114:129]
	ds_read_b128 v[156:159], v0 offset:4672
	ds_read_b128 v[186:189], v0 offset:4704
	s_waitcnt lgkmcnt(1)
	v_mfma_f32_32x32x16_bf16 v[66:81], v[156:159], v[160:163], v[66:81]
	v_mfma_f32_32x32x16_bf16 v[82:97], v[156:159], v[172:175], v[82:97]
	ds_read_b128 v[156:159], v0 offset:9280
	ds_read_b128 v[190:193], v0 offset:9312
	s_waitcnt lgkmcnt(1)
	v_mfma_f32_32x32x16_bf16 v[34:49], v[156:159], v[160:163], v[34:49]
	v_mfma_f32_32x32x16_bf16 v[50:65], v[156:159], v[172:175], v[50:65]
	ds_read_b128 v[156:159], v0 offset:13888
	ds_read_b128 v[194:197], v0 offset:13920
	s_waitcnt lgkmcnt(1)
	v_mfma_f32_32x32x16_bf16 v[2:17], v[156:159], v[160:163], v[2:17]
	v_mfma_f32_32x32x16_bf16 v[18:33], v[156:159], v[172:175], v[18:33]
	global_load_dwordx4 v[156:159], v[130:131], off offset:512
	global_load_dwordx4 v[160:163], v[132:133], off offset:512
	v_mfma_f32_32x32x16_bf16 v[98:113], v[164:167], v[168:171], v[98:113]
	v_mfma_f32_32x32x16_bf16 v[114:129], v[164:167], v[176:179], v[114:129]
	v_mfma_f32_32x32x16_bf16 v[66:81], v[186:189], v[168:171], v[66:81]
	v_mfma_f32_32x32x16_bf16 v[82:97], v[186:189], v[176:179], v[82:97]
	v_mfma_f32_32x32x16_bf16 v[34:49], v[190:193], v[168:171], v[34:49]
	v_mfma_f32_32x32x16_bf16 v[50:65], v[190:193], v[176:179], v[50:65]
	global_load_dwordx4 v[164:167], v[134:135], off offset:512
	global_load_dwordx4 v[172:175], v[136:137], off offset:512
	global_load_dwordx4 v[186:189], v[138:139], off offset:512
	global_load_dwordx4 v[190:193], v[140:141], off offset:512
	global_load_dwordx4 v[198:201], v[142:143], off offset:512
	global_load_dwordx4 v[202:205], v[144:145], off offset:512
	global_load_dwordx4 v[206:209], v[146:147], off offset:512
	global_load_dwordx4 v[210:213], v[150:151], off offset:512
	s_waitcnt lgkmcnt(0)
	v_mfma_f32_32x32x16_bf16 v[2:17], v[194:197], v[168:171], v[2:17]
	global_load_dwordx4 v[168:171], v[152:153], off offset:512
	global_load_dwordx4 v[236:239], v[154:155], off offset:512
	s_barrier
	s_waitcnt vmcnt(11)
	ds_write_b128 v148, v[156:159]
	s_waitcnt vmcnt(10)
	ds_write_b128 v148, v[160:163] offset:4608
	s_waitcnt vmcnt(9)
	ds_write_b128 v148, v[164:167] offset:9216
	s_waitcnt vmcnt(8)
	ds_write_b128 v148, v[172:175] offset:13824
	s_waitcnt vmcnt(7)
	ds_write_b128 v148, v[186:189] offset:18432
	s_waitcnt vmcnt(6)
	ds_write_b128 v148, v[190:193] offset:23040
	s_waitcnt vmcnt(5)
	ds_write_b128 v148, v[198:201] offset:27648
	s_waitcnt vmcnt(4)
	ds_write_b128 v148, v[202:205] offset:32256
	s_waitcnt vmcnt(3)
	ds_write_b128 v148, v[206:209] offset:36864
	s_waitcnt vmcnt(2)
	ds_write_b128 v148, v[210:213] offset:41472
	s_waitcnt vmcnt(1)
	ds_write_b128 v148, v[168:171] offset:46080
	s_waitcnt vmcnt(0)
	ds_write_b128 v148, v[236:239] offset:50688
	v_mfma_f32_32x32x16_bf16 v[18:33], v[194:197], v[176:179], v[18:33]
	s_waitcnt lgkmcnt(0)
	s_barrier
; #define MFMA32(a, b, c) __builtin_amdgcn_mfma_f32_32x32x16_bf16((a), (b), (c), 0, 0, 0)
; DI void gemm_mainloop_big(const bf16_t* __restrict__ A, int lda, const bf16_t* __restrict__ Bt, int ldb, int K, int m0, int n0,
;                           f32x16 (&acc)[4][2], char* smem) {
;     ...
;   for (int kt = 0; kt < nk; ++kt) {
;     if (kt + 1 < nk) {
; #pragma unroll
;       for (int i = 0; i < 8; ++i) ra[i] = *(const u32x4*)(ap + (size_t)(32 * i) * lda + (kt + 1) * 64);
; #pragma unroll
;       for (int i = 0; i < 4; ++i) rb[i] = *(const u32x4*)(bp + (size_t)(32 * i) * ldb + (kt + 1) * 64);
;     }
; #pragma unroll
;     for (int ks = 0; ks < 4; ++ks) {
;       bf16x8 af[4], bfr[2];
; #pragma unroll
;       for (int f = 0; f < 4; ++f) af[f] = *(const bf16x8*)&sa[wm * 128 + f * 32 + r][ks * 16 + half * 8];
; #pragma unroll
;       for (int f = 0; f < 2; ++f) bfr[f] = *(const bf16x8*)&sb[wn * 64 + f * 32 + r][ks * 16 + half * 8];
; #pragma unroll
;       for (int mf = 0; mf < 4; ++mf)
; #pragma unroll
;         for (int nf = 0; nf < 2; ++nf) acc[mf][nf] = MFMA32(af[mf], bfr[nf], acc[mf][nf]);
;     }
;     __syncthreads();
;     if (kt + 1 < nk) {
; #pragma unroll
;       for (int i = 0; i < 8; ++i) *(u32x4*)&sa[(tid >> 3) + 32 * i][(tid & 7) * 8] = ra[i];
; #pragma unroll
;       for (int i = 0; i < 4; ++i) *(u32x4*)&sb[(tid >> 3) + 32 * i][(tid & 7) * 8] = rb[i];
;     }
;     __syncthreads();
	ds_read_b128 v[156:159], v0
	ds_read_b128 v[160:163], v149 offset:36864
	ds_read_b128 v[164:167], v0 offset:32
	ds_read_b128 v[168:171], v149 offset:36896
	ds_read_b128 v[172:175], v149 offset:41472
	ds_read_b128 v[176:179], v149 offset:41504
	s_waitcnt lgkmcnt(4)
	v_mfma_f32_32x32x16_bf16 v[98:113], v[156:159], v[160:163], v[98:113]
	s_waitcnt lgkmcnt(1)
	v_mfma_f32_32x32x16_bf16 v[114:129], v[156:159], v[172:175], v[114:129]
	ds_read_b128 v[156:159], v0 offset:4608
	ds_read_b128 v[186:189], v0 offset:4640
	s_waitcnt lgkmcnt(1)
	v_mfma_f32_32x32x16_bf16 v[66:81], v[156:159], v[160:163], v[66:81]
	v_mfma_f32_32x32x16_bf16 v[82:97], v[156:159], v[172:175], v[82:97]
	ds_read_b128 v[156:159], v0 offset:9216
	ds_read_b128 v[190:193], v0 offset:9248
	s_waitcnt lgkmcnt(1)
	v_mfma_f32_32x32x16_bf16 v[34:49], v[156:159], v[160:163], v[34:49]
	v_mfma_f32_32x32x16_bf16 v[50:65], v[156:159], v[172:175], v[50:65]
	ds_read_b128 v[156:159], v0 offset:13824
	ds_read_b128 v[194:197], v0 offset:13856
	s_waitcnt lgkmcnt(1)
	v_mfma_f32_32x32x16_bf16 v[2:17], v[156:159], v[160:163], v[2:17]
	v_mfma_f32_32x32x16_bf16 v[18:33], v[156:159], v[172:175], v[18:33]
	v_mfma_f32_32x32x16_bf16 v[98:113], v[164:167], v[168:171], v[98:113]
	v_mfma_f32_32x32x16_bf16 v[114:129], v[164:167], v[176:179], v[114:129]
	v_mfma_f32_32x32x16_bf16 v[66:81], v[186:189], v[168:171], v[66:81]
	v_mfma_f32_32x32x16_bf16 v[82:97], v[186:189], v[176:179], v[82:97]
	v_mfma_f32_32x32x16_bf16 v[34:49], v[190:193], v[168:171], v[34:49]
	v_mfma_f32_32x32x16_bf16 v[50:65], v[190:193], v[176:179], v[50:65]
	s_waitcnt lgkmcnt(0)
	v_mfma_f32_32x32x16_bf16 v[2:17], v[194:197], v[168:171], v[2:17]
	ds_read_b128 v[156:159], v0 offset:64
	ds_read_b128 v[160:163], v149 offset:36928
	ds_read_b128 v[164:167], v0 offset:96
	ds_read_b128 v[168:171], v149 offset:36960
	v_mfma_f32_32x32x16_bf16 v[18:33], v[194:197], v[176:179], v[18:33]
	ds_read_b128 v[172:175], v149 offset:41536
	ds_read_b128 v[176:179], v149 offset:41568
	s_waitcnt lgkmcnt(4)
	v_mfma_f32_32x32x16_bf16 v[98:113], v[156:159], v[160:163], v[98:113]
	s_waitcnt lgkmcnt(1)
	v_mfma_f32_32x32x16_bf16 v[114:129], v[156:159], v[172:175], v[114:129]
	ds_read_b128 v[156:159], v0 offset:4672
	ds_read_b128 v[186:189], v0 offset:4704
	s_waitcnt lgkmcnt(1)
	v_mfma_f32_32x32x16_bf16 v[66:81], v[156:159], v[160:163], v[66:81]
	v_mfma_f32_32x32x16_bf16 v[82:97], v[156:159], v[172:175], v[82:97]
	ds_read_b128 v[156:159], v0 offset:9280
	ds_read_b128 v[190:193], v0 offset:9312
	s_waitcnt lgkmcnt(1)
	v_mfma_f32_32x32x16_bf16 v[34:49], v[156:159], v[160:163], v[34:49]
	v_mfma_f32_32x32x16_bf16 v[50:65], v[156:159], v[172:175], v[50:65]
	ds_read_b128 v[156:159], v0 offset:13888
	ds_read_b128 v[194:197], v0 offset:13920
	s_waitcnt lgkmcnt(1)
	v_mfma_f32_32x32x16_bf16 v[2:17], v[156:159], v[160:163], v[2:17]
	v_mfma_f32_32x32x16_bf16 v[18:33], v[156:159], v[172:175], v[18:33]
	global_load_dwordx4 v[156:159], v[130:131], off offset:640
	global_load_dwordx4 v[160:163], v[132:133], off offset:640
	v_mfma_f32_32x32x16_bf16 v[98:113], v[164:167], v[168:171], v[98:113]
	v_mfma_f32_32x32x16_bf16 v[114:129], v[164:167], v[176:179], v[114:129]
	v_mfma_f32_32x32x16_bf16 v[66:81], v[186:189], v[168:171], v[66:81]
	v_mfma_f32_32x32x16_bf16 v[82:97], v[186:189], v[176:179], v[82:97]
	v_mfma_f32_32x32x16_bf16 v[34:49], v[190:193], v[168:171], v[34:49]
	v_mfma_f32_32x32x16_bf16 v[50:65], v[190:193], v[176:179], v[50:65]
	global_load_dwordx4 v[164:167], v[134:135], off offset:640
	global_load_dwordx4 v[172:175], v[136:137], off offset:640
	global_load_dwordx4 v[186:189], v[138:139], off offset:640
	global_load_dwordx4 v[190:193], v[140:141], off offset:640
	global_load_dwordx4 v[198:201], v[142:143], off offset:640
	global_load_dwordx4 v[202:205], v[144:145], off offset:640
	global_load_dwordx4 v[206:209], v[146:147], off offset:640
	global_load_dwordx4 v[210:213], v[150:151], off offset:640
	s_waitcnt lgkmcnt(0)
	v_mfma_f32_32x32x16_bf16 v[2:17], v[194:197], v[168:171], v[2:17]
	global_load_dwordx4 v[168:171], v[152:153], off offset:640
	global_load_dwordx4 v[236:239], v[154:155], off offset:640
	s_barrier
	s_waitcnt vmcnt(11)
	ds_write_b128 v148, v[156:159]
	s_waitcnt vmcnt(10)
	ds_write_b128 v148, v[160:163] offset:4608
	s_waitcnt vmcnt(9)
	ds_write_b128 v148, v[164:167] offset:9216
	s_waitcnt vmcnt(8)
	ds_write_b128 v148, v[172:175] offset:13824
	s_waitcnt vmcnt(7)
	ds_write_b128 v148, v[186:189] offset:18432
	s_waitcnt vmcnt(6)
	ds_write_b128 v148, v[190:193] offset:23040
	s_waitcnt vmcnt(5)
	ds_write_b128 v148, v[198:201] offset:27648
	s_waitcnt vmcnt(4)
	ds_write_b128 v148, v[202:205] offset:32256
	s_waitcnt vmcnt(3)
	ds_write_b128 v148, v[206:209] offset:36864
	s_waitcnt vmcnt(2)
	ds_write_b128 v148, v[210:213] offset:41472
	s_waitcnt vmcnt(1)
	ds_write_b128 v148, v[168:171] offset:46080
	s_waitcnt vmcnt(0)
	ds_write_b128 v148, v[236:239] offset:50688
	v_mfma_f32_32x32x16_bf16 v[18:33], v[194:197], v[176:179], v[18:33]
	s_waitcnt lgkmcnt(0)
	s_barrier
; #define MFMA32(a, b, c) __builtin_amdgcn_mfma_f32_32x32x16_bf16((a), (b), (c), 0, 0, 0)
; DI void gemm_mainloop_big(const bf16_t* __restrict__ A, int lda, const bf16_t* __restrict__ Bt, int ldb, int K, int m0, int n0,
;                           f32x16 (&acc)[4][2], char* smem) {
;     ...
;   for (int kt = 0; kt < nk; ++kt) {
;     if (kt + 1 < nk) {
; #pragma unroll
;       for (int i = 0; i < 8; ++i) ra[i] = *(const u32x4*)(ap + (size_t)(32 * i) * lda + (kt + 1) * 64);
; #pragma unroll
;       for (int i = 0; i < 4; ++i) rb[i] = *(const u32x4*)(bp + (size_t)(32 * i) * ldb + (kt + 1) * 64);
;     }
; #pragma unroll
;     for (int ks = 0; ks < 4; ++ks) {
;       bf16x8 af[4], bfr[2];
; #pragma unroll
;       for (int f = 0; f < 4; ++f) af[f] = *(const bf16x8*)&sa[wm * 128 + f * 32 + r][ks * 16 + half * 8];
; #pragma unroll
;       for (int f = 0; f < 2; ++f) bfr[f] = *(const bf16x8*)&sb[wn * 64 + f * 32 + r][ks * 16 + half * 8];
; #pragma unroll
;       for (int mf = 0; mf < 4; ++mf)
; #pragma unroll
;         for (int nf = 0; nf < 2; ++nf) acc[mf][nf] = MFMA32(af[mf], bfr[nf], acc[mf][nf]);
;     }
;     __syncthreads();
;     if (kt + 1 < nk) {
; #pragma unroll
;       for (int i = 0; i < 8; ++i) *(u32x4*)&sa[(tid >> 3) + 32 * i][(tid & 7) * 8] = ra[i];
; #pragma unroll
;       for (int i = 0; i < 4; ++i) *(u32x4*)&sb[(tid >> 3) + 32 * i][(tid & 7) * 8] = rb[i];
;     }
;     __syncthreads();
	ds_read_b128 v[156:159], v0
	ds_read_b128 v[160:163], v149 offset:36864
	ds_read_b128 v[164:167], v0 offset:32
	ds_read_b128 v[168:171], v149 offset:36896
	ds_read_b128 v[172:175], v149 offset:41472
	ds_read_b128 v[176:179], v149 offset:41504
	s_waitcnt lgkmcnt(4)
	v_mfma_f32_32x32x16_bf16 v[98:113], v[156:159], v[160:163], v[98:113]
	s_waitcnt lgkmcnt(1)
	v_mfma_f32_32x32x16_bf16 v[114:129], v[156:159], v[172:175], v[114:129]
	ds_read_b128 v[156:159], v0 offset:4608
	ds_read_b128 v[186:189], v0 offset:4640
	s_waitcnt lgkmcnt(1)
	v_mfma_f32_32x32x16_bf16 v[66:81], v[156:159], v[160:163], v[66:81]
	v_mfma_f32_32x32x16_bf16 v[82:97], v[156:159], v[172:175], v[82:97]
	ds_read_b128 v[156:159], v0 offset:9216
	ds_read_b128 v[190:193], v0 offset:9248
	s_waitcnt lgkmcnt(1)
	v_mfma_f32_32x32x16_bf16 v[34:49], v[156:159], v[160:163], v[34:49]
	v_mfma_f32_32x32x16_bf16 v[50:65], v[156:159], v[172:175], v[50:65]
	ds_read_b128 v[156:159], v0 offset:13824
	ds_read_b128 v[194:197], v0 offset:13856
	s_waitcnt lgkmcnt(1)
	v_mfma_f32_32x32x16_bf16 v[2:17], v[156:159], v[160:163], v[2:17]
	v_mfma_f32_32x32x16_bf16 v[18:33], v[156:159], v[172:175], v[18:33]
	v_mfma_f32_32x32x16_bf16 v[98:113], v[164:167], v[168:171], v[98:113]
	v_mfma_f32_32x32x16_bf16 v[114:129], v[164:167], v[176:179], v[114:129]
	v_mfma_f32_32x32x16_bf16 v[66:81], v[186:189], v[168:171], v[66:81]
	v_mfma_f32_32x32x16_bf16 v[82:97], v[186:189], v[176:179], v[82:97]
	v_mfma_f32_32x32x16_bf16 v[34:49], v[190:193], v[168:171], v[34:49]
	v_mfma_f32_32x32x16_bf16 v[50:65], v[190:193], v[176:179], v[50:65]
	s_waitcnt lgkmcnt(0)
	v_mfma_f32_32x32x16_bf16 v[2:17], v[194:197], v[168:171], v[2:17]
	ds_read_b128 v[156:159], v0 offset:64
	ds_read_b128 v[160:163], v149 offset:36928
	ds_read_b128 v[164:167], v0 offset:96
	ds_read_b128 v[168:171], v149 offset:36960
	v_mfma_f32_32x32x16_bf16 v[18:33], v[194:197], v[176:179], v[18:33]
	ds_read_b128 v[172:175], v149 offset:41536
	ds_read_b128 v[176:179], v149 offset:41568
	s_waitcnt lgkmcnt(4)
	v_mfma_f32_32x32x16_bf16 v[98:113], v[156:159], v[160:163], v[98:113]
	s_waitcnt lgkmcnt(1)
	v_mfma_f32_32x32x16_bf16 v[114:129], v[156:159], v[172:175], v[114:129]
	ds_read_b128 v[156:159], v0 offset:4672
	ds_read_b128 v[186:189], v0 offset:4704
	s_waitcnt lgkmcnt(1)
	v_mfma_f32_32x32x16_bf16 v[66:81], v[156:159], v[160:163], v[66:81]
	v_mfma_f32_32x32x16_bf16 v[82:97], v[156:159], v[172:175], v[82:97]
	ds_read_b128 v[156:159], v0 offset:9280
	ds_read_b128 v[190:193], v0 offset:9312
	s_waitcnt lgkmcnt(1)
	v_mfma_f32_32x32x16_bf16 v[34:49], v[156:159], v[160:163], v[34:49]
	v_mfma_f32_32x32x16_bf16 v[50:65], v[156:159], v[172:175], v[50:65]
	ds_read_b128 v[156:159], v0 offset:13888
	ds_read_b128 v[194:197], v0 offset:13920
	s_waitcnt lgkmcnt(1)
	v_mfma_f32_32x32x16_bf16 v[2:17], v[156:159], v[160:163], v[2:17]
	v_mfma_f32_32x32x16_bf16 v[18:33], v[156:159], v[172:175], v[18:33]
	global_load_dwordx4 v[156:159], v[130:131], off offset:768
	global_load_dwordx4 v[160:163], v[132:133], off offset:768
	v_mfma_f32_32x32x16_bf16 v[98:113], v[164:167], v[168:171], v[98:113]
	v_mfma_f32_32x32x16_bf16 v[114:129], v[164:167], v[176:179], v[114:129]
	v_mfma_f32_32x32x16_bf16 v[66:81], v[186:189], v[168:171], v[66:81]
	v_mfma_f32_32x32x16_bf16 v[82:97], v[186:189], v[176:179], v[82:97]
	v_mfma_f32_32x32x16_bf16 v[34:49], v[190:193], v[168:171], v[34:49]
	v_mfma_f32_32x32x16_bf16 v[50:65], v[190:193], v[176:179], v[50:65]
	global_load_dwordx4 v[164:167], v[134:135], off offset:768
	global_load_dwordx4 v[172:175], v[136:137], off offset:768
	global_load_dwordx4 v[186:189], v[138:139], off offset:768
	global_load_dwordx4 v[190:193], v[140:141], off offset:768
	global_load_dwordx4 v[198:201], v[142:143], off offset:768
	global_load_dwordx4 v[202:205], v[144:145], off offset:768
	global_load_dwordx4 v[206:209], v[146:147], off offset:768
	global_load_dwordx4 v[210:213], v[150:151], off offset:768
	s_waitcnt lgkmcnt(0)
	v_mfma_f32_32x32x16_bf16 v[2:17], v[194:197], v[168:171], v[2:17]
	global_load_dwordx4 v[168:171], v[152:153], off offset:768
	global_load_dwordx4 v[236:239], v[154:155], off offset:768
	s_barrier
	s_waitcnt vmcnt(11)
	ds_write_b128 v148, v[156:159]
	s_waitcnt vmcnt(10)
	ds_write_b128 v148, v[160:163] offset:4608
	s_waitcnt vmcnt(9)
	ds_write_b128 v148, v[164:167] offset:9216
	s_waitcnt vmcnt(8)
	ds_write_b128 v148, v[172:175] offset:13824
	s_waitcnt vmcnt(7)
	ds_write_b128 v148, v[186:189] offset:18432
	s_waitcnt vmcnt(6)
	ds_write_b128 v148, v[190:193] offset:23040
	s_waitcnt vmcnt(5)
	ds_write_b128 v148, v[198:201] offset:27648
	s_waitcnt vmcnt(4)
	ds_write_b128 v148, v[202:205] offset:32256
	s_waitcnt vmcnt(3)
	ds_write_b128 v148, v[206:209] offset:36864
	s_waitcnt vmcnt(2)
	ds_write_b128 v148, v[210:213] offset:41472
	s_waitcnt vmcnt(1)
	ds_write_b128 v148, v[168:171] offset:46080
	s_waitcnt vmcnt(0)
	ds_write_b128 v148, v[236:239] offset:50688
	v_mfma_f32_32x32x16_bf16 v[18:33], v[194:197], v[176:179], v[18:33]
	s_waitcnt lgkmcnt(0)
	s_barrier
; #define MFMA32(a, b, c) __builtin_amdgcn_mfma_f32_32x32x16_bf16((a), (b), (c), 0, 0, 0)
; DI void gemm_mainloop_big(const bf16_t* __restrict__ A, int lda, const bf16_t* __restrict__ Bt, int ldb, int K, int m0, int n0,
;                           f32x16 (&acc)[4][2], char* smem) {
;     ...
;   for (int kt = 0; kt < nk; ++kt) {
;     if (kt + 1 < nk) {
; #pragma unroll
;       for (int i = 0; i < 8; ++i) ra[i] = *(const u32x4*)(ap + (size_t)(32 * i) * lda + (kt + 1) * 64);
; #pragma unroll
;       for (int i = 0; i < 4; ++i) rb[i] = *(const u32x4*)(bp + (size_t)(32 * i) * ldb + (kt + 1) * 64);
;     }
; #pragma unroll
;     for (int ks = 0; ks < 4; ++ks) {
;       bf16x8 af[4], bfr[2];
; #pragma unroll
;       for (int f = 0; f < 4; ++f) af[f] = *(const bf16x8*)&sa[wm * 128 + f * 32 + r][ks * 16 + half * 8];
; #pragma unroll
;       for (int f = 0; f < 2; ++f) bfr[f] = *(const bf16x8*)&sb[wn * 64 + f * 32 + r][ks * 16 + half * 8];
; #pragma unroll
;       for (int mf = 0; mf < 4; ++mf)
; #pragma unroll
;         for (int nf = 0; nf < 2; ++nf) acc[mf][nf] = MFMA32(af[mf], bfr[nf], acc[mf][nf]);
;     }
;     __syncthreads();
;     if (kt + 1 < nk) {
; #pragma unroll
;       for (int i = 0; i < 8; ++i) *(u32x4*)&sa[(tid >> 3) + 32 * i][(tid & 7) * 8] = ra[i];
; #pragma unroll
;       for (int i = 0; i < 4; ++i) *(u32x4*)&sb[(tid >> 3) + 32 * i][(tid & 7) * 8] = rb[i];
;     }
;     __syncthreads();
	ds_read_b128 v[156:159], v0
	ds_read_b128 v[160:163], v149 offset:36864
	ds_read_b128 v[164:167], v0 offset:32
	ds_read_b128 v[168:171], v149 offset:36896
	ds_read_b128 v[172:175], v149 offset:41472
	ds_read_b128 v[176:179], v149 offset:41504
	s_waitcnt lgkmcnt(4)
	v_mfma_f32_32x32x16_bf16 v[98:113], v[156:159], v[160:163], v[98:113]
	s_waitcnt lgkmcnt(1)
	v_mfma_f32_32x32x16_bf16 v[114:129], v[156:159], v[172:175], v[114:129]
	ds_read_b128 v[156:159], v0 offset:4608
	ds_read_b128 v[186:189], v0 offset:4640
	s_waitcnt lgkmcnt(1)
	v_mfma_f32_32x32x16_bf16 v[66:81], v[156:159], v[160:163], v[66:81]
	v_mfma_f32_32x32x16_bf16 v[82:97], v[156:159], v[172:175], v[82:97]
	ds_read_b128 v[156:159], v0 offset:9216
	ds_read_b128 v[190:193], v0 offset:9248
	s_waitcnt lgkmcnt(1)
	v_mfma_f32_32x32x16_bf16 v[34:49], v[156:159], v[160:163], v[34:49]
	v_mfma_f32_32x32x16_bf16 v[50:65], v[156:159], v[172:175], v[50:65]
	ds_read_b128 v[156:159], v0 offset:13824
	ds_read_b128 v[194:197], v0 offset:13856
	s_waitcnt lgkmcnt(1)
	v_mfma_f32_32x32x16_bf16 v[2:17], v[156:159], v[160:163], v[2:17]
	v_mfma_f32_32x32x16_bf16 v[18:33], v[156:159], v[172:175], v[18:33]
	v_mfma_f32_32x32x16_bf16 v[98:113], v[164:167], v[168:171], v[98:113]
	v_mfma_f32_32x32x16_bf16 v[114:129], v[164:167], v[176:179], v[114:129]
	v_mfma_f32_32x32x16_bf16 v[66:81], v[186:189], v[168:171], v[66:81]
	v_mfma_f32_32x32x16_bf16 v[82:97], v[186:189], v[176:179], v[82:97]
	v_mfma_f32_32x32x16_bf16 v[34:49], v[190:193], v[168:171], v[34:49]
	v_mfma_f32_32x32x16_bf16 v[50:65], v[190:193], v[176:179], v[50:65]
	s_waitcnt lgkmcnt(0)
	v_mfma_f32_32x32x16_bf16 v[2:17], v[194:197], v[168:171], v[2:17]
	ds_read_b128 v[156:159], v0 offset:64
	ds_read_b128 v[160:163], v149 offset:36928
	ds_read_b128 v[164:167], v0 offset:96
	ds_read_b128 v[168:171], v149 offset:36960
	v_mfma_f32_32x32x16_bf16 v[18:33], v[194:197], v[176:179], v[18:33]
	ds_read_b128 v[172:175], v149 offset:41536
	ds_read_b128 v[176:179], v149 offset:41568
	s_waitcnt lgkmcnt(4)
	v_mfma_f32_32x32x16_bf16 v[98:113], v[156:159], v[160:163], v[98:113]
	s_waitcnt lgkmcnt(1)
	v_mfma_f32_32x32x16_bf16 v[114:129], v[156:159], v[172:175], v[114:129]
	ds_read_b128 v[156:159], v0 offset:4672
	ds_read_b128 v[186:189], v0 offset:4704
	s_waitcnt lgkmcnt(1)
	v_mfma_f32_32x32x16_bf16 v[66:81], v[156:159], v[160:163], v[66:81]
	v_mfma_f32_32x32x16_bf16 v[82:97], v[156:159], v[172:175], v[82:97]
	ds_read_b128 v[156:159], v0 offset:9280
	ds_read_b128 v[190:193], v0 offset:9312
	s_waitcnt lgkmcnt(1)
	v_mfma_f32_32x32x16_bf16 v[34:49], v[156:159], v[160:163], v[34:49]
	v_mfma_f32_32x32x16_bf16 v[50:65], v[156:159], v[172:175], v[50:65]
	ds_read_b128 v[156:159], v0 offset:13888
	ds_read_b128 v[194:197], v0 offset:13920
	s_waitcnt lgkmcnt(1)
	v_mfma_f32_32x32x16_bf16 v[2:17], v[156:159], v[160:163], v[2:17]
	v_mfma_f32_32x32x16_bf16 v[18:33], v[156:159], v[172:175], v[18:33]
	global_load_dwordx4 v[156:159], v[130:131], off offset:896
	s_nop 0
	global_load_dwordx4 v[130:133], v[132:133], off offset:896
	v_mfma_f32_32x32x16_bf16 v[98:113], v[164:167], v[168:171], v[98:113]
	v_mfma_f32_32x32x16_bf16 v[114:129], v[164:167], v[176:179], v[114:129]
	v_mfma_f32_32x32x16_bf16 v[66:81], v[186:189], v[168:171], v[66:81]
	v_mfma_f32_32x32x16_bf16 v[82:97], v[186:189], v[176:179], v[82:97]
	v_mfma_f32_32x32x16_bf16 v[34:49], v[190:193], v[168:171], v[34:49]
	v_mfma_f32_32x32x16_bf16 v[50:65], v[190:193], v[176:179], v[50:65]
	global_load_dwordx4 v[160:163], v[134:135], off offset:896
	s_nop 0
	global_load_dwordx4 v[134:137], v[136:137], off offset:896
	s_nop 0
	global_load_dwordx4 v[164:167], v[138:139], off offset:896
	s_nop 0
	global_load_dwordx4 v[138:141], v[140:141], off offset:896
	s_nop 0
	global_load_dwordx4 v[172:175], v[142:143], off offset:896
	s_nop 0
	global_load_dwordx4 v[142:145], v[144:145], off offset:896
	s_nop 0
	global_load_dwordx4 v[186:189], v[146:147], off offset:896
	global_load_dwordx4 v[190:193], v[150:151], off offset:896
	s_waitcnt lgkmcnt(0)
	v_mfma_f32_32x32x16_bf16 v[2:17], v[194:197], v[168:171], v[2:17]
	global_load_dwordx4 v[150:153], v[152:153], off offset:896
	s_nop 0
	global_load_dwordx4 v[168:171], v[154:155], off offset:896
	s_barrier
	s_waitcnt vmcnt(11)
	ds_write_b128 v148, v[156:159]
	s_waitcnt vmcnt(10)
	ds_write_b128 v148, v[130:133] offset:4608
	s_waitcnt vmcnt(9)
	ds_write_b128 v148, v[160:163] offset:9216
	s_waitcnt vmcnt(8)
	ds_write_b128 v148, v[134:137] offset:13824
	s_waitcnt vmcnt(7)
	ds_write_b128 v148, v[164:167] offset:18432
	s_waitcnt vmcnt(6)
	ds_write_b128 v148, v[138:141] offset:23040
	s_waitcnt vmcnt(5)
	ds_write_b128 v148, v[172:175] offset:27648
	s_waitcnt vmcnt(4)
	ds_write_b128 v148, v[142:145] offset:32256
	s_waitcnt vmcnt(3)
	ds_write_b128 v148, v[186:189] offset:36864
	s_waitcnt vmcnt(2)
	ds_write_b128 v148, v[190:193] offset:41472
	s_waitcnt vmcnt(1)
	ds_write_b128 v148, v[150:153] offset:46080
	s_waitcnt vmcnt(0)
	ds_write_b128 v148, v[168:171] offset:50688
	s_waitcnt lgkmcnt(0)
	s_barrier
; #define MFMA32(a, b, c) __builtin_amdgcn_mfma_f32_32x32x16_bf16((a), (b), (c), 0, 0, 0)
; DI void gemm_mainloop_big(const bf16_t* __restrict__ A, int lda, const bf16_t* __restrict__ Bt, int ldb, int K, int m0, int n0,
;                           f32x16 (&acc)[4][2], char* smem) {
;     ...
;     for (int ks = 0; ks < 4; ++ks) {
;       bf16x8 af[4], bfr[2];
; #pragma unroll
;       for (int f = 0; f < 4; ++f) af[f] = *(const bf16x8*)&sa[wm * 128 + f * 32 + r][ks * 16 + half * 8];
; #pragma unroll
;       for (int f = 0; f < 2; ++f) bfr[f] = *(const bf16x8*)&sb[wn * 64 + f * 32 + r][ks * 16 + half * 8];
; #pragma unroll
;       for (int mf = 0; mf < 4; ++mf)
; #pragma unroll
;         for (int nf = 0; nf < 2; ++nf) acc[mf][nf] = MFMA32(af[mf], bfr[nf], acc[mf][nf]);
;     }
;     __syncthreads();
;     if (kt + 1 < nk) {
; #pragma unroll
;       for (int i = 0; i < 8; ++i) *(u32x4*)&sa[(tid >> 3) + 32 * i][(tid & 7) * 8] = ra[i];
; #pragma unroll
;       for (int i = 0; i < 4; ++i) *(u32x4*)&sb[(tid >> 3) + 32 * i][(tid & 7) * 8] = rb[i];
;     }
;     __syncthreads();
; DI void stage_half(float* st, const f32x16 (&acc)[4][2], int h, int tid) {
;   const int lane = tid & 63, w = tid >> 6, wm = w >> 1, wn = w & 1, c = lane & 31, half = lane >> 5;
;   if (wm == h) {
	ds_read_b128 v[130:133], v0
	ds_read_b128 v[134:137], v149 offset:36864
	ds_read_b128 v[138:141], v0 offset:32
	ds_read_b128 v[142:145], v149 offset:36896
	ds_read_b128 v[150:153], v149 offset:41472
	ds_read_b128 v[154:157], v149 offset:41504
	s_waitcnt lgkmcnt(4)
	v_mfma_f32_32x32x16_bf16 v[98:113], v[130:133], v[134:137], v[98:113]
	s_waitcnt lgkmcnt(1)
	v_mfma_f32_32x32x16_bf16 v[114:129], v[130:133], v[150:153], v[114:129]
	ds_read_b128 v[130:133], v0 offset:4608
	ds_read_b128 v[158:161], v0 offset:4640
	s_waitcnt lgkmcnt(1)
	v_mfma_f32_32x32x16_bf16 v[66:81], v[130:133], v[134:137], v[66:81]
	v_mfma_f32_32x32x16_bf16 v[82:97], v[130:133], v[150:153], v[82:97]
	ds_read_b128 v[130:133], v0 offset:9216
	ds_read_b128 v[162:165], v0 offset:9248
	v_mfma_f32_32x32x16_bf16 v[18:33], v[194:197], v[176:179], v[18:33]
	s_waitcnt lgkmcnt(1)
	v_mfma_f32_32x32x16_bf16 v[34:49], v[130:133], v[134:137], v[34:49]
	v_mfma_f32_32x32x16_bf16 v[50:65], v[130:133], v[150:153], v[50:65]
	ds_read_b128 v[130:133], v0 offset:13824
	ds_read_b128 v[166:169], v0 offset:13856
	s_waitcnt lgkmcnt(1)
	v_mfma_f32_32x32x16_bf16 v[2:17], v[130:133], v[134:137], v[2:17]
	v_mfma_f32_32x32x16_bf16 v[18:33], v[130:133], v[150:153], v[18:33]
	v_mfma_f32_32x32x16_bf16 v[98:113], v[138:141], v[142:145], v[98:113]
	v_mfma_f32_32x32x16_bf16 v[114:129], v[138:141], v[154:157], v[114:129]
	v_mfma_f32_32x32x16_bf16 v[66:81], v[158:161], v[142:145], v[66:81]
	v_mfma_f32_32x32x16_bf16 v[82:97], v[158:161], v[154:157], v[82:97]
	v_mfma_f32_32x32x16_bf16 v[34:49], v[162:165], v[142:145], v[34:49]
	s_waitcnt lgkmcnt(0)
	v_mfma_f32_32x32x16_bf16 v[2:17], v[166:169], v[142:145], v[2:17]
	ds_read_b128 v[130:133], v0 offset:64
	ds_read_b128 v[134:137], v149 offset:36928
	ds_read_b128 v[138:141], v0 offset:96
	ds_read_b128 v[142:145], v149 offset:36960
	ds_read_b128 v[150:153], v149 offset:41536
	ds_read_b128 v[146:149], v149 offset:41568
	v_mfma_f32_32x32x16_bf16 v[50:65], v[162:165], v[154:157], v[50:65]
	v_mfma_f32_32x32x16_bf16 v[18:33], v[166:169], v[154:157], v[18:33]
	s_waitcnt lgkmcnt(4)
	v_mfma_f32_32x32x16_bf16 v[98:113], v[130:133], v[134:137], v[98:113]
	s_waitcnt lgkmcnt(1)
	v_mfma_f32_32x32x16_bf16 v[114:129], v[130:133], v[150:153], v[114:129]
	ds_read_b128 v[130:133], v0 offset:4672
	ds_read_b128 v[154:157], v0 offset:4704
	s_waitcnt lgkmcnt(1)
	v_mfma_f32_32x32x16_bf16 v[66:81], v[130:133], v[134:137], v[66:81]
	v_mfma_f32_32x32x16_bf16 v[82:97], v[130:133], v[150:153], v[82:97]
	ds_read_b128 v[130:133], v0 offset:9280
	ds_read_b128 v[158:161], v0 offset:9312
	s_waitcnt lgkmcnt(1)
	v_mfma_f32_32x32x16_bf16 v[34:49], v[130:133], v[134:137], v[34:49]
	v_mfma_f32_32x32x16_bf16 v[50:65], v[130:133], v[150:153], v[50:65]
	ds_read_b128 v[130:133], v0 offset:13888
	ds_read_b128 v[162:165], v0 offset:13920
	v_mov_b32_e32 v0, v216
	s_waitcnt lgkmcnt(0)
	s_barrier
	s_barrier
	v_mfma_f32_32x32x16_bf16 v[2:17], v[130:133], v[134:137], v[2:17]
	s_nop 0
	v_cmp_gt_u32_e32 vcc, s31, v0
	v_mfma_f32_32x32x16_bf16 v[18:33], v[130:133], v[150:153], v[18:33]
	v_mfma_f32_32x32x16_bf16 v[98:113], v[138:141], v[142:145], v[98:113]
	v_mfma_f32_32x32x16_bf16 v[114:129], v[138:141], v[146:149], v[114:129]
	v_mfma_f32_32x32x16_bf16 v[66:81], v[154:157], v[142:145], v[66:81]
	v_mfma_f32_32x32x16_bf16 v[82:97], v[154:157], v[146:149], v[82:97]
	v_mfma_f32_32x32x16_bf16 v[34:49], v[158:161], v[142:145], v[34:49]
	v_mfma_f32_32x32x16_bf16 v[50:65], v[158:161], v[146:149], v[50:65]
	v_mfma_f32_32x32x16_bf16 v[2:17], v[162:165], v[142:145], v[2:17]
	v_mfma_f32_32x32x16_bf16 v[18:33], v[162:165], v[146:149], v[18:33]
	s_and_saveexec_b64 s[42:43], vcc
	s_cbranch_execz .LBB0_1054
; DI int crow(int i, int h) { return (i & 3) + 8 * (i >> 2) + 4 * h; }
; DI void stage_half(float* st, const f32x16 (&acc)[4][2], int h, int tid) {
;   const int lane = tid & 63, w = tid >> 6, wm = w >> 1, wn = w & 1, c = lane & 31, half = lane >> 5;
;   if (wm == h) {
; #pragma unroll
;     for (int mf = 0; mf < 4; ++mf)
; #pragma unroll
;       for (int nf = 0; nf < 2; ++nf)
; #pragma unroll
;         for (int i = 0; i < 16; ++i) st[(mf * 32 + crow(i, half)) * 132 + wn * 64 + nf * 32 + c] = acc[mf][nf][i];
;   }
; }
	v_lshrrev_b32_e32 v130, 3, v0
	v_and_b32_e32 v130, 4, v130
	v_and_b32_e32 v131, 0x5f, v0
	v_mul_u32_u24_e32 v130, 0x210, v130
	v_lshl_add_u32 v130, v131, 2, v130
	v_add_u32_e32 v131, 0x400, v130
	ds_write2_b32 v130, v98, v114 offset1:32
	ds_write2_b32 v130, v99, v115 offset0:132 offset1:164
	ds_write2_b32 v131, v100, v116 offset0:8 offset1:40
	ds_write2_b32 v131, v101, v117 offset0:140 offset1:172
	v_add_u32_e32 v131, 0x1000, v130
	ds_write2_b32 v131, v102, v118 offset0:32 offset1:64
	ds_write2_b32 v131, v103, v119 offset0:164 offset1:196
	v_add_u32_e32 v131, 0x1400, v130
	ds_write2_b32 v131, v104, v120 offset0:40 offset1:72
	ds_write2_b32 v131, v105, v121 offset0:172 offset1:204
	v_add_u32_e32 v131, 0x2000, v130
	ds_write2_b32 v131, v106, v122 offset0:64 offset1:96
	ds_write2_b32 v131, v107, v123 offset0:196 offset1:228
	v_add_u32_e32 v131, 0x2400, v130
	ds_write2_b32 v131, v108, v124 offset0:72 offset1:104
	ds_write2_b32 v131, v109, v125 offset0:204 offset1:236
	v_add_u32_e32 v131, 0x3000, v130
	ds_write2_b32 v131, v110, v126 offset0:96 offset1:128
	v_add_u32_e32 v131, 0x3200, v130
	ds_write2_b32 v131, v111, v127 offset0:100 offset1:132
	v_add_u32_e32 v131, 0x3400, v130
	ds_write2_b32 v131, v112, v128 offset0:104 offset1:136
	v_add_u32_e32 v131, 0x3600, v130
	ds_write2_b32 v131, v113, v129 offset0:108 offset1:140
	v_add_u32_e32 v131, 0x4000, v130
	ds_write2_b32 v131, v66, v82 offset0:128 offset1:160
	v_add_u32_e32 v131, 0x4400, v130
	ds_write2_b32 v131, v67, v83 offset0:4 offset1:36
	ds_write2_b32 v131, v68, v84 offset0:136 offset1:168
	v_add_u32_e32 v131, 0x4800, v130
	ds_write2_b32 v131, v69, v85 offset0:12 offset1:44
	v_add_u32_e32 v131, 0x5000, v130
	ds_write2_b32 v131, v70, v86 offset0:160 offset1:192
	v_add_u32_e32 v131, 0x5400, v130
	ds_write2_b32 v131, v71, v87 offset0:36 offset1:68
	ds_write2_b32 v131, v72, v88 offset0:168 offset1:200
	v_add_u32_e32 v131, 0x5800, v130
	ds_write2_b32 v131, v73, v89 offset0:44 offset1:76
	v_add_u32_e32 v131, 0x6000, v130
	ds_write2_b32 v131, v74, v90 offset0:192 offset1:224
	v_add_u32_e32 v131, 0x6400, v130
	ds_write2_b32 v131, v75, v91 offset0:68 offset1:100
	ds_write2_b32 v131, v76, v92 offset0:200 offset1:232
	v_add_u32_e32 v131, 0x6800, v130
	ds_write2_b32 v131, v77, v93 offset0:76 offset1:108
	v_add_u32_e32 v131, 0x7200, v130
	ds_write2_b32 v131, v78, v94 offset0:96 offset1:128
	v_add_u32_e32 v131, 0x7400, v130
	ds_write2_b32 v131, v79, v95 offset0:100 offset1:132
	v_add_u32_e32 v131, 0x7600, v130
	ds_write2_b32 v131, v80, v96 offset0:104 offset1:136
	v_add_u32_e32 v131, 0x7800, v130
	ds_write2_b32 v131, v81, v97 offset0:108 offset1:140
	v_add_u32_e32 v131, 0x8400, v130
	ds_write2_b32 v131, v34, v50 offset1:32
	ds_write2_b32 v131, v35, v51 offset0:132 offset1:164
	v_add_u32_e32 v131, 0x8800, v130
	ds_write2_b32 v131, v36, v52 offset0:8 offset1:40
	ds_write2_b32 v131, v37, v53 offset0:140 offset1:172
	v_add_u32_e32 v131, 0x9400, v130
	ds_write2_b32 v131, v38, v54 offset0:32 offset1:64
	ds_write2_b32 v131, v39, v55 offset0:164 offset1:196
	v_add_u32_e32 v131, 0x9800, v130
	ds_write2_b32 v131, v40, v56 offset0:40 offset1:72
	ds_write2_b32 v131, v41, v57 offset0:172 offset1:204
	v_add_u32_e32 v131, 0xa400, v130
	ds_write2_b32 v131, v42, v58 offset0:64 offset1:96
	ds_write2_b32 v131, v43, v59 offset0:196 offset1:228
	v_add_u32_e32 v131, 0xa800, v130
	ds_write2_b32 v131, v44, v60 offset0:72 offset1:104
	ds_write2_b32 v131, v45, v61 offset0:204 offset1:236
	v_add_u32_e32 v131, 0xb400, v130
	ds_write2_b32 v131, v46, v62 offset0:96 offset1:128
	v_add_u32_e32 v131, 0xb600, v130
	ds_write2_b32 v131, v47, v63 offset0:100 offset1:132
	v_add_u32_e32 v131, 0xb800, v130
	ds_write2_b32 v131, v48, v64 offset0:104 offset1:136
	v_add_u32_e32 v131, 0xba00, v130
	ds_write2_b32 v131, v49, v65 offset0:108 offset1:140
	v_add_u32_e32 v131, 0xc400, v130
	ds_write2_b32 v131, v2, v18 offset0:128 offset1:160
	v_add_u32_e32 v131, 0xc800, v130
	ds_write2_b32 v131, v3, v19 offset0:4 offset1:36
	ds_write2_b32 v131, v4, v20 offset0:136 offset1:168
	v_add_u32_e32 v131, 0xcc00, v130
	ds_write2_b32 v131, v5, v21 offset0:12 offset1:44
	v_add_u32_e32 v131, 0xd400, v130
	ds_write2_b32 v131, v6, v22 offset0:160 offset1:192
	v_add_u32_e32 v131, 0xd800, v130
	ds_write2_b32 v131, v7, v23 offset0:36 offset1:68
	ds_write2_b32 v131, v8, v24 offset0:168 offset1:200
	v_add_u32_e32 v131, 0xdc00, v130
	ds_write2_b32 v131, v9, v25 offset0:44 offset1:76
	v_add_u32_e32 v131, 0xe400, v130
	ds_write2_b32 v131, v10, v26 offset0:192 offset1:224
	v_add_u32_e32 v131, 0xe800, v130
	ds_write2_b32 v131, v11, v27 offset0:68 offset1:100
	ds_write2_b32 v131, v12, v28 offset0:200 offset1:232
	v_add_u32_e32 v131, 0xec00, v130
	ds_write2_b32 v131, v13, v29 offset0:76 offset1:108
	v_add_u32_e32 v131, 0xf600, v130
	ds_write2_b32 v131, v14, v30 offset0:96 offset1:128
	v_add_u32_e32 v131, 0xf800, v130
	ds_write2_b32 v131, v15, v31 offset0:100 offset1:132
	v_add_u32_e32 v131, 0xfa00, v130
	v_add_u32_e32 v130, 0xfc00, v130
	ds_write2_b32 v131, v16, v32 offset0:104 offset1:136
	ds_write2_b32 v130, v17, v33 offset0:108 offset1:140

; DI unsigned pk2(float a, float b) { f32x2 v = {a, b}; bf2_t r = __builtin_convertvector(v, bf2_t); return __builtin_bit_cast(unsigned, r); }
; DI float bf_lo(unsigned u) { return __uint_as_float(u << 16); }
; DI float bf_hi(unsigned u) { return __uint_as_float(u & 0xffff0000u); }
; DI void gemm_up_pass_big(const bf16_t* Y, const bf16_t* W, const bf16_t* __restrict__ GBR, int gcol0, bf16_t* __restrict__ MG, bool first,
;                          int mt, int nt, char* smem) {
;     ...
;     const int r = tid >> 4, ch = tid & 15;
; #pragma unroll 2
;     for (int ps = 0; ps < 8; ++ps) {
;       const int row = ps * 16 + r;
;       const float4 a0 = *(const float4*)(st + row * 132 + ch * 8), a1 = *(const float4*)(st + row * 132 + ch * 8 + 4);
;       const size_t grow = (size_t)(m0 + h * 128 + row);
;       const u32x4 gv = *(const u32x4*)(GBR + grow * 2048 + gcol0 + n0 + ch * 8);
;       float v[8];
;       v[0] = bf_lo(gv.x) * a0.x; v[1] = bf_hi(gv.x) * a0.y; v[2] = bf_lo(gv.y) * a0.z; v[3] = bf_hi(gv.y) * a0.w;
;       v[4] = bf_lo(gv.z) * a1.x; v[5] = bf_hi(gv.z) * a1.y; v[6] = bf_lo(gv.w) * a1.z; v[7] = bf_hi(gv.w) * a1.w;
;       bf16_t* mp = MG + grow * 1024 + n0 + ch * 8;
;       if (!first) {
;         const u32x4 pv = *(const u32x4*)mp;
;         v[0] += bf_lo(pv.x); v[1] += bf_hi(pv.x); v[2] += bf_lo(pv.y); v[3] += bf_hi(pv.y);
;         v[4] += bf_lo(pv.z); v[5] += bf_hi(pv.z); v[6] += bf_lo(pv.w); v[7] += bf_hi(pv.w);
;       }
;       u32x4 ov; ov.x = pk2(v[0], v[1]); ov.y = pk2(v[2], v[3]); ov.z = pk2(v[4], v[5]); ov.w = pk2(v[6], v[7]);
;       *(u32x4*)mp = ov;
;     }
.LBB0_1055:
	v_lshl_add_u64 v[194:195], v[136:137], 0, s[28:29]
	v_lshl_add_u64 v[196:197], v[132:133], 0, s[28:29]
	v_lshl_add_u64 v[202:203], v[134:135], 0, s[28:29]
	v_lshl_add_u64 v[204:205], v[130:131], 0, s[28:29]
	v_lshl_add_u64 v[198:199], v[134:135], 0, s[28:29]
	v_lshl_add_u64 v[200:201], v[130:131], 0, s[28:29]
	global_load_dwordx4 v[138:141], v[194:195], off
	global_load_dwordx4 v[154:157], v[198:199], off
	v_lshl_add_u64 v[194:195], v[194:195], 0, s[92:93]
	v_lshl_add_u64 v[198:199], v[198:199], 0, s[38:39]
	global_load_dwordx4 v[142:145], v[196:197], off
	global_load_dwordx4 v[158:161], v[200:201], off
	v_lshl_add_u64 v[196:197], v[196:197], 0, s[92:93]
	v_lshl_add_u64 v[200:201], v[200:201], 0, s[38:39]
	global_load_dwordx4 v[146:149], v[194:195], off
	global_load_dwordx4 v[162:165], v[198:199], off
	v_lshl_add_u64 v[194:195], v[194:195], 0, s[92:93]
	v_lshl_add_u64 v[198:199], v[198:199], 0, s[38:39]
	global_load_dwordx4 v[150:153], v[196:197], off
	global_load_dwordx4 v[166:169], v[200:201], off
	v_lshl_add_u64 v[196:197], v[196:197], 0, s[92:93]
	v_lshl_add_u64 v[200:201], v[200:201], 0, s[38:39]
	ds_read_b128 v[172:175], v0 offset:0
	ds_read_b128 v[176:179], v0 offset:16
	s_waitcnt vmcnt(6) lgkmcnt(0)
	v_lshlrev_b32_e32 v190, 16, v138
	v_and_b32_e32 v191, 0xffff0000, v138
	v_lshlrev_b32_e32 v192, 16, v154
	v_and_b32_e32 v193, 0xffff0000, v154
	v_pk_fma_f32 v[172:173], v[172:173], v[190:191], v[192:193]
	v_lshlrev_b32_e32 v190, 16, v139
	v_and_b32_e32 v191, 0xffff0000, v139
	v_lshlrev_b32_e32 v192, 16, v155
	v_and_b32_e32 v193, 0xffff0000, v155
	v_pk_fma_f32 v[174:175], v[174:175], v[190:191], v[192:193]
	v_lshlrev_b32_e32 v190, 16, v140
	v_and_b32_e32 v191, 0xffff0000, v140
	v_lshlrev_b32_e32 v192, 16, v156
	v_and_b32_e32 v193, 0xffff0000, v156
	v_pk_fma_f32 v[176:177], v[176:177], v[190:191], v[192:193]
	v_lshlrev_b32_e32 v190, 16, v141
	v_and_b32_e32 v191, 0xffff0000, v141
	v_lshlrev_b32_e32 v192, 16, v157
	v_and_b32_e32 v193, 0xffff0000, v157
	v_pk_fma_f32 v[178:179], v[178:179], v[190:191], v[192:193]
	v_cvt_pk_bf16_f32 v186, v172, v173
	v_cvt_pk_bf16_f32 v187, v174, v175
	v_cvt_pk_bf16_f32 v188, v176, v177
	v_cvt_pk_bf16_f32 v189, v178, v179
	global_store_dwordx4 v[202:203], v[186:189], off
	s_nop 1
	v_lshl_add_u64 v[202:203], v[202:203], 0, s[38:39]
	ds_read_b128 v[172:175], v0 offset:8448
	ds_read_b128 v[176:179], v0 offset:8464
	s_waitcnt vmcnt(5) lgkmcnt(0)
	v_lshlrev_b32_e32 v190, 16, v142
	v_and_b32_e32 v191, 0xffff0000, v142
	v_lshlrev_b32_e32 v192, 16, v158
	v_and_b32_e32 v193, 0xffff0000, v158
	v_pk_fma_f32 v[172:173], v[172:173], v[190:191], v[192:193]
	v_lshlrev_b32_e32 v190, 16, v143
	v_and_b32_e32 v191, 0xffff0000, v143
	v_lshlrev_b32_e32 v192, 16, v159
	v_and_b32_e32 v193, 0xffff0000, v159
	v_pk_fma_f32 v[174:175], v[174:175], v[190:191], v[192:193]
	v_lshlrev_b32_e32 v190, 16, v144
	v_and_b32_e32 v191, 0xffff0000, v144
	v_lshlrev_b32_e32 v192, 16, v160
	v_and_b32_e32 v193, 0xffff0000, v160
	v_pk_fma_f32 v[176:177], v[176:177], v[190:191], v[192:193]
	v_lshlrev_b32_e32 v190, 16, v145
	v_and_b32_e32 v191, 0xffff0000, v145
	v_lshlrev_b32_e32 v192, 16, v161
	v_and_b32_e32 v193, 0xffff0000, v161
	v_pk_fma_f32 v[178:179], v[178:179], v[190:191], v[192:193]
	v_cvt_pk_bf16_f32 v186, v172, v173
	v_cvt_pk_bf16_f32 v187, v174, v175
	v_cvt_pk_bf16_f32 v188, v176, v177
	v_cvt_pk_bf16_f32 v189, v178, v179
	global_store_dwordx4 v[204:205], v[186:189], off
	s_nop 1
	v_lshl_add_u64 v[204:205], v[204:205], 0, s[38:39]
	ds_read_b128 v[172:175], v0 offset:16896
	ds_read_b128 v[176:179], v0 offset:16912
	s_waitcnt vmcnt(4) lgkmcnt(0)
	v_lshlrev_b32_e32 v190, 16, v146
	v_and_b32_e32 v191, 0xffff0000, v146
	v_lshlrev_b32_e32 v192, 16, v162
	v_and_b32_e32 v193, 0xffff0000, v162
	v_pk_fma_f32 v[172:173], v[172:173], v[190:191], v[192:193]
	v_lshlrev_b32_e32 v190, 16, v147
	v_and_b32_e32 v191, 0xffff0000, v147
	v_lshlrev_b32_e32 v192, 16, v163
	v_and_b32_e32 v193, 0xffff0000, v163
	v_pk_fma_f32 v[174:175], v[174:175], v[190:191], v[192:193]
	v_lshlrev_b32_e32 v190, 16, v148
	v_and_b32_e32 v191, 0xffff0000, v148
	v_lshlrev_b32_e32 v192, 16, v164
	v_and_b32_e32 v193, 0xffff0000, v164
	v_pk_fma_f32 v[176:177], v[176:177], v[190:191], v[192:193]
	v_lshlrev_b32_e32 v190, 16, v149
	v_and_b32_e32 v191, 0xffff0000, v149
	v_lshlrev_b32_e32 v192, 16, v165
	v_and_b32_e32 v193, 0xffff0000, v165
	v_pk_fma_f32 v[178:179], v[178:179], v[190:191], v[192:193]
	v_cvt_pk_bf16_f32 v186, v172, v173
	v_cvt_pk_bf16_f32 v187, v174, v175
	v_cvt_pk_bf16_f32 v188, v176, v177
	v_cvt_pk_bf16_f32 v189, v178, v179
	global_store_dwordx4 v[202:203], v[186:189], off
	s_nop 1
	v_lshl_add_u64 v[202:203], v[202:203], 0, s[38:39]
	ds_read_b128 v[172:175], v0 offset:25344
	ds_read_b128 v[176:179], v0 offset:25360
	s_waitcnt vmcnt(3) lgkmcnt(0)
; DI unsigned pk2(float a, float b) { f32x2 v = {a, b}; bf2_t r = __builtin_convertvector(v, bf2_t); return __builtin_bit_cast(unsigned, r); }
; DI float bf_lo(unsigned u) { return __uint_as_float(u << 16); }
; DI float bf_hi(unsigned u) { return __uint_as_float(u & 0xffff0000u); }
; DI void gemm_up_pass_big(const bf16_t* Y, const bf16_t* W, const bf16_t* __restrict__ GBR, int gcol0, bf16_t* __restrict__ MG, bool first,
;                          int mt, int nt, char* smem) {
;     ...
;     const int r = tid >> 4, ch = tid & 15;
; #pragma unroll 2
;     for (int ps = 0; ps < 8; ++ps) {
;       const int row = ps * 16 + r;
;       const float4 a0 = *(const float4*)(st + row * 132 + ch * 8), a1 = *(const float4*)(st + row * 132 + ch * 8 + 4);
;       const size_t grow = (size_t)(m0 + h * 128 + row);
;       const u32x4 gv = *(const u32x4*)(GBR + grow * 2048 + gcol0 + n0 + ch * 8);
;       float v[8];
;       v[0] = bf_lo(gv.x) * a0.x; v[1] = bf_hi(gv.x) * a0.y; v[2] = bf_lo(gv.y) * a0.z; v[3] = bf_hi(gv.y) * a0.w;
;       v[4] = bf_lo(gv.z) * a1.x; v[5] = bf_hi(gv.z) * a1.y; v[6] = bf_lo(gv.w) * a1.z; v[7] = bf_hi(gv.w) * a1.w;
;       bf16_t* mp = MG + grow * 1024 + n0 + ch * 8;
;       if (!first) {
;         const u32x4 pv = *(const u32x4*)mp;
;         v[0] += bf_lo(pv.x); v[1] += bf_hi(pv.x); v[2] += bf_lo(pv.y); v[3] += bf_hi(pv.y);
;         v[4] += bf_lo(pv.z); v[5] += bf_hi(pv.z); v[6] += bf_lo(pv.w); v[7] += bf_hi(pv.w);
;       }
;       u32x4 ov; ov.x = pk2(v[0], v[1]); ov.y = pk2(v[2], v[3]); ov.z = pk2(v[4], v[5]); ov.w = pk2(v[6], v[7]);
;       *(u32x4*)mp = ov;
;     }
;     __syncthreads();
	v_lshlrev_b32_e32 v190, 16, v150
	v_and_b32_e32 v191, 0xffff0000, v150
	v_lshlrev_b32_e32 v192, 16, v166
	v_and_b32_e32 v193, 0xffff0000, v166
	v_pk_fma_f32 v[172:173], v[172:173], v[190:191], v[192:193]
	v_lshlrev_b32_e32 v190, 16, v151
	v_and_b32_e32 v191, 0xffff0000, v151
	v_lshlrev_b32_e32 v192, 16, v167
	v_and_b32_e32 v193, 0xffff0000, v167
	v_pk_fma_f32 v[174:175], v[174:175], v[190:191], v[192:193]
	v_lshlrev_b32_e32 v190, 16, v152
	v_and_b32_e32 v191, 0xffff0000, v152
	v_lshlrev_b32_e32 v192, 16, v168
	v_and_b32_e32 v193, 0xffff0000, v168
	v_pk_fma_f32 v[176:177], v[176:177], v[190:191], v[192:193]
	v_lshlrev_b32_e32 v190, 16, v153
	v_and_b32_e32 v191, 0xffff0000, v153
	v_lshlrev_b32_e32 v192, 16, v169
	v_and_b32_e32 v193, 0xffff0000, v169
	v_pk_fma_f32 v[178:179], v[178:179], v[190:191], v[192:193]
	v_cvt_pk_bf16_f32 v186, v172, v173
	v_cvt_pk_bf16_f32 v187, v174, v175
	v_cvt_pk_bf16_f32 v188, v176, v177
	v_cvt_pk_bf16_f32 v189, v178, v179
	global_store_dwordx4 v[204:205], v[186:189], off
	s_nop 1
	v_lshl_add_u64 v[204:205], v[204:205], 0, s[38:39]
	global_load_dwordx4 v[138:141], v[194:195], off
	global_load_dwordx4 v[154:157], v[198:199], off
	v_lshl_add_u64 v[194:195], v[194:195], 0, s[92:93]
	v_lshl_add_u64 v[198:199], v[198:199], 0, s[38:39]
	global_load_dwordx4 v[142:145], v[196:197], off
	global_load_dwordx4 v[158:161], v[200:201], off
	v_lshl_add_u64 v[196:197], v[196:197], 0, s[92:93]
	v_lshl_add_u64 v[200:201], v[200:201], 0, s[38:39]
	global_load_dwordx4 v[146:149], v[194:195], off
	global_load_dwordx4 v[162:165], v[198:199], off
	v_lshl_add_u64 v[194:195], v[194:195], 0, s[92:93]
	v_lshl_add_u64 v[198:199], v[198:199], 0, s[38:39]
	global_load_dwordx4 v[150:153], v[196:197], off
	global_load_dwordx4 v[166:169], v[200:201], off
	v_lshl_add_u64 v[196:197], v[196:197], 0, s[92:93]
	v_lshl_add_u64 v[200:201], v[200:201], 0, s[38:39]
	ds_read_b128 v[172:175], v0 offset:33792
	ds_read_b128 v[176:179], v0 offset:33808
	s_waitcnt vmcnt(6) lgkmcnt(0)
	v_lshlrev_b32_e32 v190, 16, v138
	v_and_b32_e32 v191, 0xffff0000, v138
	v_lshlrev_b32_e32 v192, 16, v154
	v_and_b32_e32 v193, 0xffff0000, v154
	v_pk_fma_f32 v[172:173], v[172:173], v[190:191], v[192:193]
	v_lshlrev_b32_e32 v190, 16, v139
	v_and_b32_e32 v191, 0xffff0000, v139
	v_lshlrev_b32_e32 v192, 16, v155
	v_and_b32_e32 v193, 0xffff0000, v155
	v_pk_fma_f32 v[174:175], v[174:175], v[190:191], v[192:193]
	v_lshlrev_b32_e32 v190, 16, v140
	v_and_b32_e32 v191, 0xffff0000, v140
	v_lshlrev_b32_e32 v192, 16, v156
	v_and_b32_e32 v193, 0xffff0000, v156
	v_pk_fma_f32 v[176:177], v[176:177], v[190:191], v[192:193]
	v_lshlrev_b32_e32 v190, 16, v141
	v_and_b32_e32 v191, 0xffff0000, v141
	v_lshlrev_b32_e32 v192, 16, v157
	v_and_b32_e32 v193, 0xffff0000, v157
	v_pk_fma_f32 v[178:179], v[178:179], v[190:191], v[192:193]
	v_cvt_pk_bf16_f32 v186, v172, v173
	v_cvt_pk_bf16_f32 v187, v174, v175
	v_cvt_pk_bf16_f32 v188, v176, v177
	v_cvt_pk_bf16_f32 v189, v178, v179
	global_store_dwordx4 v[202:203], v[186:189], off
	s_nop 1
	v_lshl_add_u64 v[202:203], v[202:203], 0, s[38:39]
	ds_read_b128 v[172:175], v0 offset:42240
	ds_read_b128 v[176:179], v0 offset:42256
	s_waitcnt vmcnt(5) lgkmcnt(0)
	v_lshlrev_b32_e32 v190, 16, v142
	v_and_b32_e32 v191, 0xffff0000, v142
	v_lshlrev_b32_e32 v192, 16, v158
	v_and_b32_e32 v193, 0xffff0000, v158
	v_pk_fma_f32 v[172:173], v[172:173], v[190:191], v[192:193]
	v_lshlrev_b32_e32 v190, 16, v143
	v_and_b32_e32 v191, 0xffff0000, v143
	v_lshlrev_b32_e32 v192, 16, v159
	v_and_b32_e32 v193, 0xffff0000, v159
	v_pk_fma_f32 v[174:175], v[174:175], v[190:191], v[192:193]
	v_lshlrev_b32_e32 v190, 16, v144
	v_and_b32_e32 v191, 0xffff0000, v144
	v_lshlrev_b32_e32 v192, 16, v160
	v_and_b32_e32 v193, 0xffff0000, v160
	v_pk_fma_f32 v[176:177], v[176:177], v[190:191], v[192:193]
	v_lshlrev_b32_e32 v190, 16, v145
	v_and_b32_e32 v191, 0xffff0000, v145
	v_lshlrev_b32_e32 v192, 16, v161
	v_and_b32_e32 v193, 0xffff0000, v161
	v_pk_fma_f32 v[178:179], v[178:179], v[190:191], v[192:193]
	v_cvt_pk_bf16_f32 v186, v172, v173
	v_cvt_pk_bf16_f32 v187, v174, v175
	v_cvt_pk_bf16_f32 v188, v176, v177
	v_cvt_pk_bf16_f32 v189, v178, v179
	global_store_dwordx4 v[204:205], v[186:189], off
	s_nop 1
	v_lshl_add_u64 v[204:205], v[204:205], 0, s[38:39]
	ds_read_b128 v[172:175], v0 offset:50688
	ds_read_b128 v[176:179], v0 offset:50704
	s_waitcnt vmcnt(4) lgkmcnt(0)
	v_lshlrev_b32_e32 v190, 16, v146
	v_and_b32_e32 v191, 0xffff0000, v146
	v_lshlrev_b32_e32 v192, 16, v162
	v_and_b32_e32 v193, 0xffff0000, v162
	v_pk_fma_f32 v[172:173], v[172:173], v[190:191], v[192:193]
	v_lshlrev_b32_e32 v190, 16, v147
	v_and_b32_e32 v191, 0xffff0000, v147
	v_lshlrev_b32_e32 v192, 16, v163
	v_and_b32_e32 v193, 0xffff0000, v163
	v_pk_fma_f32 v[174:175], v[174:175], v[190:191], v[192:193]
	v_lshlrev_b32_e32 v190, 16, v148
	v_and_b32_e32 v191, 0xffff0000, v148
	v_lshlrev_b32_e32 v192, 16, v164
	v_and_b32_e32 v193, 0xffff0000, v164
	v_pk_fma_f32 v[176:177], v[176:177], v[190:191], v[192:193]
	v_lshlrev_b32_e32 v190, 16, v149
	v_and_b32_e32 v191, 0xffff0000, v149
	v_lshlrev_b32_e32 v192, 16, v165
	v_and_b32_e32 v193, 0xffff0000, v165
	v_pk_fma_f32 v[178:179], v[178:179], v[190:191], v[192:193]
	v_cvt_pk_bf16_f32 v186, v172, v173
	v_cvt_pk_bf16_f32 v187, v174, v175
	v_cvt_pk_bf16_f32 v188, v176, v177
	v_cvt_pk_bf16_f32 v189, v178, v179
	global_store_dwordx4 v[202:203], v[186:189], off
	s_nop 1
	v_lshl_add_u64 v[202:203], v[202:203], 0, s[38:39]
	ds_read_b128 v[172:175], v0 offset:59136
	ds_read_b128 v[176:179], v0 offset:59152
	s_waitcnt vmcnt(3) lgkmcnt(0)
	v_lshlrev_b32_e32 v190, 16, v150
	v_and_b32_e32 v191, 0xffff0000, v150
	v_lshlrev_b32_e32 v192, 16, v166
	v_and_b32_e32 v193, 0xffff0000, v166
	v_pk_fma_f32 v[172:173], v[172:173], v[190:191], v[192:193]
	v_lshlrev_b32_e32 v190, 16, v151
	v_and_b32_e32 v191, 0xffff0000, v151
	v_lshlrev_b32_e32 v192, 16, v167
	v_and_b32_e32 v193, 0xffff0000, v167
	v_pk_fma_f32 v[174:175], v[174:175], v[190:191], v[192:193]
	v_lshlrev_b32_e32 v190, 16, v152
	v_and_b32_e32 v191, 0xffff0000, v152
	v_lshlrev_b32_e32 v192, 16, v168
	v_and_b32_e32 v193, 0xffff0000, v168
	v_pk_fma_f32 v[176:177], v[176:177], v[190:191], v[192:193]
	v_lshlrev_b32_e32 v190, 16, v153
	v_and_b32_e32 v191, 0xffff0000, v153
	v_lshlrev_b32_e32 v192, 16, v169
	v_and_b32_e32 v193, 0xffff0000, v169
	v_pk_fma_f32 v[178:179], v[178:179], v[190:191], v[192:193]
	v_cvt_pk_bf16_f32 v186, v172, v173
	v_cvt_pk_bf16_f32 v187, v174, v175
	v_cvt_pk_bf16_f32 v188, v176, v177
	v_cvt_pk_bf16_f32 v189, v178, v179
	global_store_dwordx4 v[204:205], v[186:189], off
	s_nop 1
	v_lshl_add_u64 v[204:205], v[204:205], 0, s[38:39]
	v_mov_b32_e32 v0, v216
	s_barrier
; DI int crow(int i, int h) { return (i & 3) + 8 * (i >> 2) + 4 * h; }
; DI void stage_half(float* st, const f32x16 (&acc)[4][2], int h, int tid) {
;   const int lane = tid & 63, w = tid >> 6, wm = w >> 1, wn = w & 1, c = lane & 31, half = lane >> 5;
;   if (wm == h) {
; #pragma unroll
;     for (int mf = 0; mf < 4; ++mf)
; #pragma unroll
;       for (int nf = 0; nf < 2; ++nf)
; #pragma unroll
;         for (int i = 0; i < 16; ++i) st[(mf * 32 + crow(i, half)) * 132 + wn * 64 + nf * 32 + c] = acc[mf][nf][i];
;   }
; }
	s_nop 0
	v_and_b32_e32 v130, 0xffffff80, v0
	v_cmp_eq_u32_e32 vcc, s31, v130
	s_and_saveexec_b64 s[42:43], vcc
	s_cbranch_execz .LBB0_1058
	v_lshrrev_b32_e32 v130, 3, v0
	v_and_b32_e32 v130, 4, v130
	v_and_b32_e32 v131, 0x5f, v0
	v_mul_u32_u24_e32 v130, 0x210, v130
	v_lshl_add_u32 v130, v131, 2, v130
	ds_write2_b32 v130, v98, v114 offset1:32
	ds_write2_b32 v130, v99, v115 offset0:132 offset1:164
	v_add_u32_e32 v98, 0x400, v130
	ds_write2_b32 v98, v100, v116 offset0:8 offset1:40
	ds_write2_b32 v98, v101, v117 offset0:140 offset1:172
	v_add_u32_e32 v98, 0x1000, v130
	ds_write2_b32 v98, v102, v118 offset0:32 offset1:64
	ds_write2_b32 v98, v103, v119 offset0:164 offset1:196
	v_add_u32_e32 v98, 0x1400, v130
	ds_write2_b32 v98, v104, v120 offset0:40 offset1:72
	ds_write2_b32 v98, v105, v121 offset0:172 offset1:204
	v_add_u32_e32 v98, 0x2000, v130
	ds_write2_b32 v98, v106, v122 offset0:64 offset1:96
	ds_write2_b32 v98, v107, v123 offset0:196 offset1:228
	v_add_u32_e32 v98, 0x2400, v130
	ds_write2_b32 v98, v108, v124 offset0:72 offset1:104
	ds_write2_b32 v98, v109, v125 offset0:204 offset1:236
	v_add_u32_e32 v98, 0x3000, v130
	ds_write2_b32 v98, v110, v126 offset0:96 offset1:128
	v_add_u32_e32 v98, 0x3200, v130
	ds_write2_b32 v98, v111, v127 offset0:100 offset1:132
	v_add_u32_e32 v98, 0x3400, v130
	ds_write2_b32 v98, v112, v128 offset0:104 offset1:136
	v_add_u32_e32 v98, 0x3600, v130
	ds_write2_b32 v98, v113, v129 offset0:108 offset1:140
	v_add_u32_e32 v98, 0x4000, v130
	ds_write2_b32 v98, v66, v82 offset0:128 offset1:160
	v_add_u32_e32 v66, 0x4400, v130
	ds_write2_b32 v66, v67, v83 offset0:4 offset1:36
	ds_write2_b32 v66, v68, v84 offset0:136 offset1:168
	v_add_u32_e32 v66, 0x4800, v130
	ds_write2_b32 v66, v69, v85 offset0:12 offset1:44
	v_add_u32_e32 v66, 0x5000, v130
	ds_write2_b32 v66, v70, v86 offset0:160 offset1:192
	v_add_u32_e32 v66, 0x5400, v130
	ds_write2_b32 v66, v71, v87 offset0:36 offset1:68
	ds_write2_b32 v66, v72, v88 offset0:168 offset1:200
	v_add_u32_e32 v66, 0x5800, v130
	ds_write2_b32 v66, v73, v89 offset0:44 offset1:76
	v_add_u32_e32 v66, 0x6000, v130
	ds_write2_b32 v66, v74, v90 offset0:192 offset1:224
	v_add_u32_e32 v66, 0x6400, v130
	ds_write2_b32 v66, v75, v91 offset0:68 offset1:100
	ds_write2_b32 v66, v76, v92 offset0:200 offset1:232
	v_add_u32_e32 v66, 0x6800, v130
	ds_write2_b32 v66, v77, v93 offset0:76 offset1:108
	v_add_u32_e32 v66, 0x7200, v130
	ds_write2_b32 v66, v78, v94 offset0:96 offset1:128
	v_add_u32_e32 v66, 0x7400, v130
	ds_write2_b32 v66, v79, v95 offset0:100 offset1:132
	v_add_u32_e32 v66, 0x7600, v130
	ds_write2_b32 v66, v80, v96 offset0:104 offset1:136
	v_add_u32_e32 v66, 0x7800, v130
	ds_write2_b32 v66, v81, v97 offset0:108 offset1:140
	v_add_u32_e32 v66, 0x8400, v130
	ds_write2_b32 v66, v34, v50 offset1:32
	ds_write2_b32 v66, v35, v51 offset0:132 offset1:164
	v_add_u32_e32 v34, 0x8800, v130
	ds_write2_b32 v34, v36, v52 offset0:8 offset1:40
	ds_write2_b32 v34, v37, v53 offset0:140 offset1:172
	v_add_u32_e32 v34, 0x9400, v130
	ds_write2_b32 v34, v38, v54 offset0:32 offset1:64
	ds_write2_b32 v34, v39, v55 offset0:164 offset1:196
	v_add_u32_e32 v34, 0x9800, v130
	ds_write2_b32 v34, v40, v56 offset0:40 offset1:72
	ds_write2_b32 v34, v41, v57 offset0:172 offset1:204
	v_add_u32_e32 v34, 0xa400, v130
	ds_write2_b32 v34, v42, v58 offset0:64 offset1:96
	ds_write2_b32 v34, v43, v59 offset0:196 offset1:228
	v_add_u32_e32 v34, 0xa800, v130
	ds_write2_b32 v34, v44, v60 offset0:72 offset1:104
	ds_write2_b32 v34, v45, v61 offset0:204 offset1:236
	v_add_u32_e32 v34, 0xb400, v130
	ds_write2_b32 v34, v46, v62 offset0:96 offset1:128
	v_add_u32_e32 v34, 0xb600, v130
	ds_write2_b32 v34, v47, v63 offset0:100 offset1:132
	v_add_u32_e32 v34, 0xb800, v130
	ds_write2_b32 v34, v48, v64 offset0:104 offset1:136
	v_add_u32_e32 v34, 0xba00, v130
	ds_write2_b32 v34, v49, v65 offset0:108 offset1:140
	v_add_u32_e32 v34, 0xc400, v130
	ds_write2_b32 v34, v2, v18 offset0:128 offset1:160
	v_add_u32_e32 v2, 0xc800, v130
	ds_write2_b32 v2, v3, v19 offset0:4 offset1:36
	ds_write2_b32 v2, v4, v20 offset0:136 offset1:168
	v_add_u32_e32 v2, 0xcc00, v130
	ds_write2_b32 v2, v5, v21 offset0:12 offset1:44
	v_add_u32_e32 v2, 0xd400, v130
	ds_write2_b32 v2, v6, v22 offset0:160 offset1:192
	v_add_u32_e32 v2, 0xd800, v130
	ds_write2_b32 v2, v7, v23 offset0:36 offset1:68
	ds_write2_b32 v2, v8, v24 offset0:168 offset1:200
	v_add_u32_e32 v2, 0xdc00, v130
	ds_write2_b32 v2, v9, v25 offset0:44 offset1:76
	v_add_u32_e32 v2, 0xe400, v130
	ds_write2_b32 v2, v10, v26 offset0:192 offset1:224
	v_add_u32_e32 v2, 0xe800, v130
	ds_write2_b32 v2, v11, v27 offset0:68 offset1:100
	ds_write2_b32 v2, v12, v28 offset0:200 offset1:232
	v_add_u32_e32 v2, 0xec00, v130
	ds_write2_b32 v2, v13, v29 offset0:76 offset1:108
	v_add_u32_e32 v2, 0xf600, v130
	ds_write2_b32 v2, v14, v30 offset0:96 offset1:128
	v_add_u32_e32 v2, 0xf800, v130
	ds_write2_b32 v2, v15, v31 offset0:100 offset1:132
	v_add_u32_e32 v2, 0xfa00, v130
	ds_write2_b32 v2, v16, v32 offset0:104 offset1:136
	v_add_u32_e32 v2, 0xfc00, v130
	ds_write2_b32 v2, v17, v33 offset0:108 offset1:140

; DI unsigned pk2(float a, float b) { f32x2 v = {a, b}; bf2_t r = __builtin_convertvector(v, bf2_t); return __builtin_bit_cast(unsigned, r); }
; DI float bf_lo(unsigned u) { return __uint_as_float(u << 16); }
; DI float bf_hi(unsigned u) { return __uint_as_float(u & 0xffff0000u); }
; DI void gemm_up_pass_big(const bf16_t* Y, const bf16_t* W, const bf16_t* __restrict__ GBR, int gcol0, bf16_t* __restrict__ MG, bool first,
;                          int mt, int nt, char* smem) {
;     ...
;     const int r = tid >> 4, ch = tid & 15;
; #pragma unroll 2
;     for (int ps = 0; ps < 8; ++ps) {
;       const int row = ps * 16 + r;
;       const float4 a0 = *(const float4*)(st + row * 132 + ch * 8), a1 = *(const float4*)(st + row * 132 + ch * 8 + 4);
;       const size_t grow = (size_t)(m0 + h * 128 + row);
;       const u32x4 gv = *(const u32x4*)(GBR + grow * 2048 + gcol0 + n0 + ch * 8);
;       float v[8];
;       v[0] = bf_lo(gv.x) * a0.x; v[1] = bf_hi(gv.x) * a0.y; v[2] = bf_lo(gv.y) * a0.z; v[3] = bf_hi(gv.y) * a0.w;
;       v[4] = bf_lo(gv.z) * a1.x; v[5] = bf_hi(gv.z) * a1.y; v[6] = bf_lo(gv.w) * a1.z; v[7] = bf_hi(gv.w) * a1.w;
;       bf16_t* mp = MG + grow * 1024 + n0 + ch * 8;
;       if (!first) {
;         const u32x4 pv = *(const u32x4*)mp;
;         v[0] += bf_lo(pv.x); v[1] += bf_hi(pv.x); v[2] += bf_lo(pv.y); v[3] += bf_hi(pv.y);
;         v[4] += bf_lo(pv.z); v[5] += bf_hi(pv.z); v[6] += bf_lo(pv.w); v[7] += bf_hi(pv.w);
;       }
;       u32x4 ov; ov.x = pk2(v[0], v[1]); ov.y = pk2(v[2], v[3]); ov.z = pk2(v[4], v[5]); ov.w = pk2(v[6], v[7]);
;       *(u32x4*)mp = ov;
;     }
.LBB0_1059:
	v_lshl_add_u64 v[194:195], v[8:9], 0, s[28:29]
	v_lshl_add_u64 v[196:197], v[4:5], 0, s[28:29]
	v_lshl_add_u64 v[202:203], v[6:7], 0, s[28:29]
	v_lshl_add_u64 v[204:205], v[2:3], 0, s[28:29]
	v_lshl_add_u64 v[198:199], v[6:7], 0, s[28:29]
	v_lshl_add_u64 v[200:201], v[2:3], 0, s[28:29]
	global_load_dwordx4 v[138:141], v[194:195], off
	global_load_dwordx4 v[154:157], v[198:199], off
	v_lshl_add_u64 v[194:195], v[194:195], 0, s[92:93]
	v_lshl_add_u64 v[198:199], v[198:199], 0, s[38:39]
	global_load_dwordx4 v[142:145], v[196:197], off
	global_load_dwordx4 v[158:161], v[200:201], off
	v_lshl_add_u64 v[196:197], v[196:197], 0, s[92:93]
	v_lshl_add_u64 v[200:201], v[200:201], 0, s[38:39]
	global_load_dwordx4 v[146:149], v[194:195], off
	global_load_dwordx4 v[162:165], v[198:199], off
	v_lshl_add_u64 v[194:195], v[194:195], 0, s[92:93]
	v_lshl_add_u64 v[198:199], v[198:199], 0, s[38:39]
	global_load_dwordx4 v[150:153], v[196:197], off
	global_load_dwordx4 v[166:169], v[200:201], off
	v_lshl_add_u64 v[196:197], v[196:197], 0, s[92:93]
	v_lshl_add_u64 v[200:201], v[200:201], 0, s[38:39]
	ds_read_b128 v[172:175], v0 offset:0
	ds_read_b128 v[176:179], v0 offset:16
	s_waitcnt vmcnt(6) lgkmcnt(0)
	v_lshlrev_b32_e32 v190, 16, v138
	v_and_b32_e32 v191, 0xffff0000, v138
	v_lshlrev_b32_e32 v192, 16, v154
	v_and_b32_e32 v193, 0xffff0000, v154
	v_pk_fma_f32 v[172:173], v[172:173], v[190:191], v[192:193]
	v_lshlrev_b32_e32 v190, 16, v139
	v_and_b32_e32 v191, 0xffff0000, v139
	v_lshlrev_b32_e32 v192, 16, v155
	v_and_b32_e32 v193, 0xffff0000, v155
	v_pk_fma_f32 v[174:175], v[174:175], v[190:191], v[192:193]
	v_lshlrev_b32_e32 v190, 16, v140
	v_and_b32_e32 v191, 0xffff0000, v140
	v_lshlrev_b32_e32 v192, 16, v156
	v_and_b32_e32 v193, 0xffff0000, v156
	v_pk_fma_f32 v[176:177], v[176:177], v[190:191], v[192:193]
	v_lshlrev_b32_e32 v190, 16, v141
	v_and_b32_e32 v191, 0xffff0000, v141
	v_lshlrev_b32_e32 v192, 16, v157
	v_and_b32_e32 v193, 0xffff0000, v157
	v_pk_fma_f32 v[178:179], v[178:179], v[190:191], v[192:193]
	v_cvt_pk_bf16_f32 v186, v172, v173
	v_cvt_pk_bf16_f32 v187, v174, v175
	v_cvt_pk_bf16_f32 v188, v176, v177
	v_cvt_pk_bf16_f32 v189, v178, v179
	global_store_dwordx4 v[202:203], v[186:189], off
	s_nop 1
	v_lshl_add_u64 v[202:203], v[202:203], 0, s[38:39]
	ds_read_b128 v[172:175], v0 offset:8448
	ds_read_b128 v[176:179], v0 offset:8464
	s_waitcnt vmcnt(5) lgkmcnt(0)
	v_lshlrev_b32_e32 v190, 16, v142
	v_and_b32_e32 v191, 0xffff0000, v142
	v_lshlrev_b32_e32 v192, 16, v158
	v_and_b32_e32 v193, 0xffff0000, v158
	v_pk_fma_f32 v[172:173], v[172:173], v[190:191], v[192:193]
	v_lshlrev_b32_e32 v190, 16, v143
	v_and_b32_e32 v191, 0xffff0000, v143
	v_lshlrev_b32_e32 v192, 16, v159
	v_and_b32_e32 v193, 0xffff0000, v159
	v_pk_fma_f32 v[174:175], v[174:175], v[190:191], v[192:193]
	v_lshlrev_b32_e32 v190, 16, v144
	v_and_b32_e32 v191, 0xffff0000, v144
	v_lshlrev_b32_e32 v192, 16, v160
	v_and_b32_e32 v193, 0xffff0000, v160
	v_pk_fma_f32 v[176:177], v[176:177], v[190:191], v[192:193]
	v_lshlrev_b32_e32 v190, 16, v145
	v_and_b32_e32 v191, 0xffff0000, v145
	v_lshlrev_b32_e32 v192, 16, v161
	v_and_b32_e32 v193, 0xffff0000, v161
	v_pk_fma_f32 v[178:179], v[178:179], v[190:191], v[192:193]
	v_cvt_pk_bf16_f32 v186, v172, v173
	v_cvt_pk_bf16_f32 v187, v174, v175
	v_cvt_pk_bf16_f32 v188, v176, v177
	v_cvt_pk_bf16_f32 v189, v178, v179
	global_store_dwordx4 v[204:205], v[186:189], off
	s_nop 1
	v_lshl_add_u64 v[204:205], v[204:205], 0, s[38:39]
	ds_read_b128 v[172:175], v0 offset:16896
	ds_read_b128 v[176:179], v0 offset:16912
	s_waitcnt vmcnt(4) lgkmcnt(0)
	v_lshlrev_b32_e32 v190, 16, v146
	v_and_b32_e32 v191, 0xffff0000, v146
	v_lshlrev_b32_e32 v192, 16, v162
	v_and_b32_e32 v193, 0xffff0000, v162
	v_pk_fma_f32 v[172:173], v[172:173], v[190:191], v[192:193]
	v_lshlrev_b32_e32 v190, 16, v147
	v_and_b32_e32 v191, 0xffff0000, v147
	v_lshlrev_b32_e32 v192, 16, v163
	v_and_b32_e32 v193, 0xffff0000, v163
	v_pk_fma_f32 v[174:175], v[174:175], v[190:191], v[192:193]
	v_lshlrev_b32_e32 v190, 16, v148
	v_and_b32_e32 v191, 0xffff0000, v148
	v_lshlrev_b32_e32 v192, 16, v164
	v_and_b32_e32 v193, 0xffff0000, v164
	v_pk_fma_f32 v[176:177], v[176:177], v[190:191], v[192:193]
	v_lshlrev_b32_e32 v190, 16, v149
	v_and_b32_e32 v191, 0xffff0000, v149
	v_lshlrev_b32_e32 v192, 16, v165
	v_and_b32_e32 v193, 0xffff0000, v165
	v_pk_fma_f32 v[178:179], v[178:179], v[190:191], v[192:193]
	v_cvt_pk_bf16_f32 v186, v172, v173
	v_cvt_pk_bf16_f32 v187, v174, v175
	v_cvt_pk_bf16_f32 v188, v176, v177
	v_cvt_pk_bf16_f32 v189, v178, v179
	global_store_dwordx4 v[202:203], v[186:189], off
	s_nop 1
	v_lshl_add_u64 v[202:203], v[202:203], 0, s[38:39]
	ds_read_b128 v[172:175], v0 offset:25344
	ds_read_b128 v[176:179], v0 offset:25360
	s_waitcnt vmcnt(3) lgkmcnt(0)
; DI unsigned pk2(float a, float b) { f32x2 v = {a, b}; bf2_t r = __builtin_convertvector(v, bf2_t); return __builtin_bit_cast(unsigned, r); }
; DI float bf_lo(unsigned u) { return __uint_as_float(u << 16); }
; DI float bf_hi(unsigned u) { return __uint_as_float(u & 0xffff0000u); }
; DI void gemm_up_pass_big(const bf16_t* Y, const bf16_t* W, const bf16_t* __restrict__ GBR, int gcol0, bf16_t* __restrict__ MG, bool first,
;                          int mt, int nt, char* smem) {
;     ...
;     const int r = tid >> 4, ch = tid & 15;
; #pragma unroll 2
;     for (int ps = 0; ps < 8; ++ps) {
;       const int row = ps * 16 + r;
;       const float4 a0 = *(const float4*)(st + row * 132 + ch * 8), a1 = *(const float4*)(st + row * 132 + ch * 8 + 4);
;       const size_t grow = (size_t)(m0 + h * 128 + row);
;       const u32x4 gv = *(const u32x4*)(GBR + grow * 2048 + gcol0 + n0 + ch * 8);
;       float v[8];
;       v[0] = bf_lo(gv.x) * a0.x; v[1] = bf_hi(gv.x) * a0.y; v[2] = bf_lo(gv.y) * a0.z; v[3] = bf_hi(gv.y) * a0.w;
;       v[4] = bf_lo(gv.z) * a1.x; v[5] = bf_hi(gv.z) * a1.y; v[6] = bf_lo(gv.w) * a1.z; v[7] = bf_hi(gv.w) * a1.w;
;       bf16_t* mp = MG + grow * 1024 + n0 + ch * 8;
;       if (!first) {
;         const u32x4 pv = *(const u32x4*)mp;
;         v[0] += bf_lo(pv.x); v[1] += bf_hi(pv.x); v[2] += bf_lo(pv.y); v[3] += bf_hi(pv.y);
;         v[4] += bf_lo(pv.z); v[5] += bf_hi(pv.z); v[6] += bf_lo(pv.w); v[7] += bf_hi(pv.w);
;       }
;       u32x4 ov; ov.x = pk2(v[0], v[1]); ov.y = pk2(v[2], v[3]); ov.z = pk2(v[4], v[5]); ov.w = pk2(v[6], v[7]);
;       *(u32x4*)mp = ov;
;     }
;     __syncthreads();
	v_lshlrev_b32_e32 v190, 16, v150
	v_and_b32_e32 v191, 0xffff0000, v150
	v_lshlrev_b32_e32 v192, 16, v166
	v_and_b32_e32 v193, 0xffff0000, v166
	v_pk_fma_f32 v[172:173], v[172:173], v[190:191], v[192:193]
	v_lshlrev_b32_e32 v190, 16, v151
	v_and_b32_e32 v191, 0xffff0000, v151
	v_lshlrev_b32_e32 v192, 16, v167
	v_and_b32_e32 v193, 0xffff0000, v167
	v_pk_fma_f32 v[174:175], v[174:175], v[190:191], v[192:193]
	v_lshlrev_b32_e32 v190, 16, v152
	v_and_b32_e32 v191, 0xffff0000, v152
	v_lshlrev_b32_e32 v192, 16, v168
	v_and_b32_e32 v193, 0xffff0000, v168
	v_pk_fma_f32 v[176:177], v[176:177], v[190:191], v[192:193]
	v_lshlrev_b32_e32 v190, 16, v153
	v_and_b32_e32 v191, 0xffff0000, v153
	v_lshlrev_b32_e32 v192, 16, v169
	v_and_b32_e32 v193, 0xffff0000, v169
	v_pk_fma_f32 v[178:179], v[178:179], v[190:191], v[192:193]
	v_cvt_pk_bf16_f32 v186, v172, v173
	v_cvt_pk_bf16_f32 v187, v174, v175
	v_cvt_pk_bf16_f32 v188, v176, v177
	v_cvt_pk_bf16_f32 v189, v178, v179
	global_store_dwordx4 v[204:205], v[186:189], off
	s_nop 1
	v_lshl_add_u64 v[204:205], v[204:205], 0, s[38:39]
	global_load_dwordx4 v[138:141], v[194:195], off
	global_load_dwordx4 v[154:157], v[198:199], off
	v_lshl_add_u64 v[194:195], v[194:195], 0, s[92:93]
	v_lshl_add_u64 v[198:199], v[198:199], 0, s[38:39]
	global_load_dwordx4 v[142:145], v[196:197], off
	global_load_dwordx4 v[158:161], v[200:201], off
	v_lshl_add_u64 v[196:197], v[196:197], 0, s[92:93]
	v_lshl_add_u64 v[200:201], v[200:201], 0, s[38:39]
	global_load_dwordx4 v[146:149], v[194:195], off
	global_load_dwordx4 v[162:165], v[198:199], off
	v_lshl_add_u64 v[194:195], v[194:195], 0, s[92:93]
	v_lshl_add_u64 v[198:199], v[198:199], 0, s[38:39]
	global_load_dwordx4 v[150:153], v[196:197], off
	global_load_dwordx4 v[166:169], v[200:201], off
	v_lshl_add_u64 v[196:197], v[196:197], 0, s[92:93]
	v_lshl_add_u64 v[200:201], v[200:201], 0, s[38:39]
	ds_read_b128 v[172:175], v0 offset:33792
	ds_read_b128 v[176:179], v0 offset:33808
	s_waitcnt vmcnt(6) lgkmcnt(0)
	v_lshlrev_b32_e32 v190, 16, v138
	v_and_b32_e32 v191, 0xffff0000, v138
	v_lshlrev_b32_e32 v192, 16, v154
	v_and_b32_e32 v193, 0xffff0000, v154
	v_pk_fma_f32 v[172:173], v[172:173], v[190:191], v[192:193]
	v_lshlrev_b32_e32 v190, 16, v139
	v_and_b32_e32 v191, 0xffff0000, v139
	v_lshlrev_b32_e32 v192, 16, v155
	v_and_b32_e32 v193, 0xffff0000, v155
	v_pk_fma_f32 v[174:175], v[174:175], v[190:191], v[192:193]
	v_lshlrev_b32_e32 v190, 16, v140
	v_and_b32_e32 v191, 0xffff0000, v140
	v_lshlrev_b32_e32 v192, 16, v156
	v_and_b32_e32 v193, 0xffff0000, v156
	v_pk_fma_f32 v[176:177], v[176:177], v[190:191], v[192:193]
	v_lshlrev_b32_e32 v190, 16, v141
	v_and_b32_e32 v191, 0xffff0000, v141
	v_lshlrev_b32_e32 v192, 16, v157
	v_and_b32_e32 v193, 0xffff0000, v157
	v_pk_fma_f32 v[178:179], v[178:179], v[190:191], v[192:193]
	v_cvt_pk_bf16_f32 v186, v172, v173
	v_cvt_pk_bf16_f32 v187, v174, v175
	v_cvt_pk_bf16_f32 v188, v176, v177
	v_cvt_pk_bf16_f32 v189, v178, v179
	global_store_dwordx4 v[202:203], v[186:189], off
	s_nop 1
	v_lshl_add_u64 v[202:203], v[202:203], 0, s[38:39]
	ds_read_b128 v[172:175], v0 offset:42240
	ds_read_b128 v[176:179], v0 offset:42256
	s_waitcnt vmcnt(5) lgkmcnt(0)
	v_lshlrev_b32_e32 v190, 16, v142
	v_and_b32_e32 v191, 0xffff0000, v142
	v_lshlrev_b32_e32 v192, 16, v158
	v_and_b32_e32 v193, 0xffff0000, v158
	v_pk_fma_f32 v[172:173], v[172:173], v[190:191], v[192:193]
	v_lshlrev_b32_e32 v190, 16, v143
	v_and_b32_e32 v191, 0xffff0000, v143
	v_lshlrev_b32_e32 v192, 16, v159
	v_and_b32_e32 v193, 0xffff0000, v159
	v_pk_fma_f32 v[174:175], v[174:175], v[190:191], v[192:193]
	v_lshlrev_b32_e32 v190, 16, v144
	v_and_b32_e32 v191, 0xffff0000, v144
	v_lshlrev_b32_e32 v192, 16, v160
	v_and_b32_e32 v193, 0xffff0000, v160
	v_pk_fma_f32 v[176:177], v[176:177], v[190:191], v[192:193]
	v_lshlrev_b32_e32 v190, 16, v145
	v_and_b32_e32 v191, 0xffff0000, v145
	v_lshlrev_b32_e32 v192, 16, v161
	v_and_b32_e32 v193, 0xffff0000, v161
	v_pk_fma_f32 v[178:179], v[178:179], v[190:191], v[192:193]
	v_cvt_pk_bf16_f32 v186, v172, v173
	v_cvt_pk_bf16_f32 v187, v174, v175
	v_cvt_pk_bf16_f32 v188, v176, v177
	v_cvt_pk_bf16_f32 v189, v178, v179
	global_store_dwordx4 v[204:205], v[186:189], off
	s_nop 1
	v_lshl_add_u64 v[204:205], v[204:205], 0, s[38:39]
	ds_read_b128 v[172:175], v0 offset:50688
	ds_read_b128 v[176:179], v0 offset:50704
	s_waitcnt vmcnt(4) lgkmcnt(0)
	v_lshlrev_b32_e32 v190, 16, v146
	v_and_b32_e32 v191, 0xffff0000, v146
	v_lshlrev_b32_e32 v192, 16, v162
	v_and_b32_e32 v193, 0xffff0000, v162
	v_pk_fma_f32 v[172:173], v[172:173], v[190:191], v[192:193]
	v_lshlrev_b32_e32 v190, 16, v147
	v_and_b32_e32 v191, 0xffff0000, v147
	v_lshlrev_b32_e32 v192, 16, v163
	v_and_b32_e32 v193, 0xffff0000, v163
	v_pk_fma_f32 v[174:175], v[174:175], v[190:191], v[192:193]
	v_lshlrev_b32_e32 v190, 16, v148
	v_and_b32_e32 v191, 0xffff0000, v148
	v_lshlrev_b32_e32 v192, 16, v164
	v_and_b32_e32 v193, 0xffff0000, v164
	v_pk_fma_f32 v[176:177], v[176:177], v[190:191], v[192:193]
	v_lshlrev_b32_e32 v190, 16, v149
	v_and_b32_e32 v191, 0xffff0000, v149
	v_lshlrev_b32_e32 v192, 16, v165
	v_and_b32_e32 v193, 0xffff0000, v165
	v_pk_fma_f32 v[178:179], v[178:179], v[190:191], v[192:193]
	v_cvt_pk_bf16_f32 v186, v172, v173
	v_cvt_pk_bf16_f32 v187, v174, v175
	v_cvt_pk_bf16_f32 v188, v176, v177
	v_cvt_pk_bf16_f32 v189, v178, v179
	global_store_dwordx4 v[202:203], v[186:189], off
	s_nop 1
	v_lshl_add_u64 v[202:203], v[202:203], 0, s[38:39]
	ds_read_b128 v[172:175], v0 offset:59136
	ds_read_b128 v[176:179], v0 offset:59152
	s_waitcnt vmcnt(3) lgkmcnt(0)
	v_lshlrev_b32_e32 v190, 16, v150
	v_and_b32_e32 v191, 0xffff0000, v150
	v_lshlrev_b32_e32 v192, 16, v166
	v_and_b32_e32 v193, 0xffff0000, v166
	v_pk_fma_f32 v[172:173], v[172:173], v[190:191], v[192:193]
	v_lshlrev_b32_e32 v190, 16, v151
	v_and_b32_e32 v191, 0xffff0000, v151
	v_lshlrev_b32_e32 v192, 16, v167
	v_and_b32_e32 v193, 0xffff0000, v167
	v_pk_fma_f32 v[174:175], v[174:175], v[190:191], v[192:193]
	v_lshlrev_b32_e32 v190, 16, v152
	v_and_b32_e32 v191, 0xffff0000, v152
	v_lshlrev_b32_e32 v192, 16, v168
	v_and_b32_e32 v193, 0xffff0000, v168
	v_pk_fma_f32 v[176:177], v[176:177], v[190:191], v[192:193]
	v_lshlrev_b32_e32 v190, 16, v153
	v_and_b32_e32 v191, 0xffff0000, v153
	v_lshlrev_b32_e32 v192, 16, v169
	v_and_b32_e32 v193, 0xffff0000, v169
	v_pk_fma_f32 v[178:179], v[178:179], v[190:191], v[192:193]
	v_cvt_pk_bf16_f32 v186, v172, v173
	v_cvt_pk_bf16_f32 v187, v174, v175
	v_cvt_pk_bf16_f32 v188, v176, v177
	v_cvt_pk_bf16_f32 v189, v178, v179
	global_store_dwordx4 v[204:205], v[186:189], off
	s_nop 1
	v_lshl_add_u64 v[204:205], v[204:205], 0, s[38:39]
	s_barrier
	s_branch .LBB0_1042
